# speedup vs baseline: 1.0254x; 1.0073x over previous
; template <int AMODE, bool SWAP>
; DI void gemm_core(const u16* __restrict__ A, int lda, const u16* __restrict__ Bt, int ldb, int K, int m0, int n0, int acol,
;                   f32x16 (&acc)[2][2], u16* sA, u16* sB) {
;     ...
;   gload(0, ra[0], rb[0]);
;   for (int kt = 0; kt < nk; ++kt) {
;     stage(ra[0], rb[0]);
;     __syncthreads();
;     if (kt + 1 < nk) gload(kt + 1, ra[0], rb[0]);
; __global__ void __launch_bounds__(512, 2) mega(Params P) {
;     ...
;         const int m0 = mt_ * 128, n0 = nt_ * 128;
;         f32x16 acc[2][2];
;         u32 gatepk[2][2][8];
;         zero_acc(acc);
;         gemm_core<0, true>(UO, DM, WPG, DM, DM, m0, n0, 0, acc, sA, sB);
.LBB0_1556:
	v_readlane_b32 s10, v255, 59
	v_mov_b32_e32 v32, v159
	s_lshl_b32 s22, s10, 7
	v_readlane_b32 s10, v255, 60
	s_lshl_b32 s21, s10, 7
	v_bfe_u32 v33, v32, 3, 5
	v_or_b32_e32 v0, 32, v33
	v_or_b32_e32 v12, s22, v0
	v_or_b32_e32 v14, s21, v0
	v_or_b32_e32 v0, 64, v33
	v_or_b32_e32 v8, s21, v33
	v_or_b32_e32 v18, s22, v0
	v_or_b32_e32 v20, s21, v0
	v_or_b32_e32 v0, 0x60, v33
	v_or_b32_e32 v2, s22, v33
	v_ashrrev_i32_e32 v9, 31, v8
	v_readlane_b32 s12, v252, 42
	v_or_b32_e32 v24, s22, v0
	v_or_b32_e32 v28, s21, v0
	v_ashrrev_i32_e32 v3, 31, v2
	v_readlane_b32 s10, v255, 39
	v_lshlrev_b64 v[8:9], 11, v[8:9]
	v_readlane_b32 s13, v252, 43
	v_ashrrev_i32_e32 v13, 31, v12
	v_ashrrev_i32_e32 v15, 31, v14
	v_ashrrev_i32_e32 v19, 31, v18
	v_ashrrev_i32_e32 v21, 31, v20
	v_ashrrev_i32_e32 v25, 31, v24
	v_ashrrev_i32_e32 v29, 31, v28
	v_lshlrev_b32_e32 v0, 4, v32
	v_lshlrev_b64 v[4:5], 11, v[2:3]
	v_readlane_b32 s11, v255, 40
	v_lshl_add_u64 v[10:11], s[12:13], 0, v[8:9]
	v_lshlrev_b64 v[12:13], 11, v[12:13]
	v_lshlrev_b64 v[14:15], 11, v[14:15]
	v_lshlrev_b64 v[18:19], 11, v[18:19]
	v_lshlrev_b64 v[20:21], 11, v[20:21]
	v_lshlrev_b64 v[24:25], 11, v[24:25]
	v_lshlrev_b64 v[28:29], 11, v[28:29]
	v_and_b32_e32 v0, 0x70, v0
	v_lshl_add_u64 v[6:7], s[10:11], 0, v[4:5]
	v_lshl_add_u64 v[12:13], s[10:11], 0, v[12:13]
	v_lshl_add_u64 v[16:17], s[12:13], 0, v[14:15]
	v_lshl_add_u64 v[18:19], s[10:11], 0, v[18:19]
	v_lshl_add_u64 v[22:23], s[12:13], 0, v[20:21]
	v_lshl_add_u64 v[26:27], s[10:11], 0, v[24:25]
	v_lshl_add_u64 v[30:31], s[12:13], 0, v[28:29]
	v_lshl_add_u64 v[10:11], v[10:11], 0, v[0:1]
	v_lshl_add_u64 v[6:7], v[6:7], 0, v[0:1]
	v_lshl_add_u64 v[12:13], v[12:13], 0, v[0:1]
	v_lshl_add_u64 v[16:17], v[16:17], 0, v[0:1]
	v_lshl_add_u64 v[18:19], v[18:19], 0, v[0:1]
	v_lshl_add_u64 v[22:23], v[22:23], 0, v[0:1]
	v_lshl_add_u64 v[26:27], v[26:27], 0, v[0:1]
	v_lshl_add_u64 v[30:31], v[30:31], 0, v[0:1]
	global_load_dwordx4 v[86:89], v[10:11], off
	global_load_dwordx4 v[94:97], v[6:7], off
	global_load_dwordx4 v[78:81], v[16:17], off
	global_load_dwordx4 v[90:93], v[12:13], off
	global_load_dwordx4 v[66:69], v[22:23], off
	global_load_dwordx4 v[82:85], v[18:19], off
	global_load_dwordx4 v[70:73], v[30:31], off
	global_load_dwordx4 v[74:77], v[26:27], off
	v_mul_u32_u24_e32 v6, 0x48, v33
	v_lshlrev_b32_e32 v6, 1, v6
	v_and_b32_e32 v3, 31, v32
	v_add3_u32 v119, s42, v0, v6
	v_lshrrev_b32_e32 v6, 1, v32
	v_and_or_b32 v3, v6, 64, v3
	v_mul_u32_u24_e32 v3, 0x90, v3
	v_and_b32_e32 v6, 16, v6
	v_readlane_b32 s10, v255, 2
	v_add3_u32 v114, s42, v3, v6
	v_and_b32_e32 v3, 0x5f, v32
	v_or_b32_e32 v4, v4, v0
	v_readlane_b32 s11, v255, 3
	v_mul_u32_u24_e32 v3, 0x90, v3
	v_add3_u32 v115, s42, v3, v6
	v_lshl_add_u64 v[98:99], s[10:11], 0, v[4:5]
	v_or_b32_e32 v4, 32, v2
	v_or_b32_e32 v2, 64, v2
	v_ashrrev_i32_e32 v3, 31, v2
	v_ashrrev_i32_e32 v5, 31, v4
	v_lshlrev_b64 v[2:3], 11, v[2:3]
	v_readlane_b32 s12, v255, 20
	v_lshlrev_b64 v[4:5], 11, v[4:5]
	v_or_b32_e32 v2, v2, v0
	v_or_b32_e32 v8, v8, v0
	v_readlane_b32 s13, v255, 21
	v_or_b32_e32 v4, v4, v0
	v_or_b32_e32 v14, v14, v0
	v_lshl_add_u64 v[106:107], s[10:11], 0, v[2:3]
	v_or_b32_e32 v20, v20, v0
	v_or_b32_e32 v24, v24, v0
	v_or_b32_e32 v28, v28, v0
	v_mov_b32_e32 v2, 0
	v_add_u32_e32 v118, 0x1200, v119
	v_add_u32_e32 v117, 0x2400, v119
	v_add_u32_e32 v116, 0x3600, v119
	v_lshl_add_u64 v[100:101], s[12:13], 0, v[8:9]
	v_lshl_add_u64 v[102:103], s[10:11], 0, v[4:5]
	v_lshl_add_u64 v[104:105], s[12:13], 0, v[14:15]
	v_lshl_add_u64 v[108:109], s[12:13], 0, v[20:21]
	v_lshl_add_u64 v[110:111], s[10:11], 0, v[24:25]
	v_lshl_add_u64 v[112:113], s[12:13], 0, v[28:29]
	s_mov_b64 s[30:31], 0
	v_mov_b32_e32 v3, v2
	v_mov_b32_e32 v4, v2
	v_mov_b32_e32 v5, v2
	v_mov_b32_e32 v6, v2
	v_mov_b32_e32 v7, v2
	v_mov_b32_e32 v8, v2
	v_mov_b32_e32 v9, v2
	v_mov_b32_e32 v10, v2
	v_mov_b32_e32 v11, v2
	v_mov_b32_e32 v12, v2
	v_mov_b32_e32 v13, v2
	v_mov_b32_e32 v14, v2
	v_mov_b32_e32 v15, v2
	v_mov_b32_e32 v16, v2
	v_mov_b32_e32 v17, v2
	v_mov_b32_e32 v18, v2
	v_mov_b32_e32 v19, v2
	v_mov_b32_e32 v20, v2
	v_mov_b32_e32 v21, v2
	v_mov_b32_e32 v22, v2
	v_mov_b32_e32 v23, v2
	v_mov_b32_e32 v24, v2
	v_mov_b32_e32 v25, v2
	v_mov_b32_e32 v26, v2
	v_mov_b32_e32 v27, v2
	v_mov_b32_e32 v28, v2
	v_mov_b32_e32 v29, v2
	v_mov_b32_e32 v30, v2
	v_mov_b32_e32 v31, v2
	v_mov_b32_e32 v32, v2
	v_mov_b32_e32 v33, v2
	v_mov_b32_e32 v34, v2
	v_mov_b32_e32 v35, v2
	v_mov_b32_e32 v36, v2
	v_mov_b32_e32 v37, v2
	v_mov_b32_e32 v38, v2
	v_mov_b32_e32 v39, v2
	v_mov_b32_e32 v40, v2
	v_mov_b32_e32 v41, v2
	v_mov_b32_e32 v42, v2
	v_mov_b32_e32 v43, v2
	v_mov_b32_e32 v44, v2
	v_mov_b32_e32 v45, v2
	v_mov_b32_e32 v46, v2
	v_mov_b32_e32 v47, v2
	v_mov_b32_e32 v48, v2
	v_mov_b32_e32 v49, v2
	v_mov_b32_e32 v50, v2
	v_mov_b32_e32 v51, v2
	v_mov_b32_e32 v52, v2
	v_mov_b32_e32 v53, v2
	v_mov_b32_e32 v54, v2
	v_mov_b32_e32 v55, v2
	v_mov_b32_e32 v56, v2
	v_mov_b32_e32 v57, v2
	v_mov_b32_e32 v58, v2
	v_mov_b32_e32 v59, v2
	v_mov_b32_e32 v60, v2
	v_mov_b32_e32 v61, v2
	v_mov_b32_e32 v62, v2
	v_mov_b32_e32 v63, v2
	v_mov_b32_e32 v64, v2
	v_mov_b32_e32 v65, v2
	v_add_u32_e32 v170, 0x14000, v119
	v_add_u32_e32 v171, 0x14000, v118
	v_add_u32_e32 v172, 0x14000, v117
	v_add_u32_e32 v173, 0x14000, v116
	v_add_u32_e32 v174, 0x14000, v114
	v_add_u32_e32 v175, 0x14000, v115
	s_mov_b64 s[30:31], 0x80
	global_load_dwordx4 v[202:205], v[98:99], off
	global_load_dwordx4 v[206:209], v[100:101], off
	global_load_dwordx4 v[210:213], v[102:103], off
	global_load_dwordx4 v[214:217], v[104:105], off
	global_load_dwordx4 v[218:221], v[106:107], off
	global_load_dwordx4 v[222:225], v[108:109], off
	global_load_dwordx4 v[152:155], v[110:111], off
	global_load_dwordx4 v[160:163], v[112:113], off
	s_waitcnt vmcnt(8)
	ds_write_b128 v170, v[94:97]
	ds_write_b128 v170, v[86:89] offset:18432
	ds_write_b128 v171, v[90:93]
	ds_write_b128 v171, v[78:81] offset:18432
	ds_write_b128 v172, v[82:85]
	ds_write_b128 v172, v[66:69] offset:18432
	ds_write_b128 v173, v[74:77]
	ds_write_b128 v173, v[70:73] offset:18432
	s_waitcnt lgkmcnt(0)
	s_barrier
	global_load_dwordx4 v[94:97], v[98:99], off offset:128
	global_load_dwordx4 v[86:89], v[100:101], off offset:128
	global_load_dwordx4 v[90:93], v[102:103], off offset:128
	global_load_dwordx4 v[78:81], v[104:105], off offset:128
	global_load_dwordx4 v[82:85], v[106:107], off offset:128
	global_load_dwordx4 v[66:69], v[108:109], off offset:128
	global_load_dwordx4 v[74:77], v[110:111], off offset:128
	global_load_dwordx4 v[70:73], v[112:113], off offset:128
	v_lshl_add_u64 v[98:99], v[98:99], 0, s[30:31]
	v_lshl_add_u64 v[100:101], v[100:101], 0, s[30:31]
	v_lshl_add_u64 v[102:103], v[102:103], 0, s[30:31]
	v_lshl_add_u64 v[104:105], v[104:105], 0, s[30:31]
	v_lshl_add_u64 v[106:107], v[106:107], 0, s[30:31]
	v_lshl_add_u64 v[108:109], v[108:109], 0, s[30:31]
	v_lshl_add_u64 v[110:111], v[110:111], 0, s[30:31]
	v_lshl_add_u64 v[112:113], v[112:113], 0, s[30:31]
	s_mov_b32 s100, 0
; #define MFMA32(a, b, c) __builtin_amdgcn_mfma_f32_32x32x16_bf16((a), (b), (c), 0, 0, 0)
; template <int AMODE, bool SWAP>
; DI void gemm_core(const u16* __restrict__ A, int lda, const u16* __restrict__ Bt, int ldb, int K, int m0, int n0, int acol,
;                   f32x16 (&acc)[2][2], u16* sA, u16* sB) {
;     ...
;   auto stage = [&](const u32x4 (&xa)[4], const u32x4 (&xb)[4]) {
; #pragma unroll
;     for (int i = 0; i < 4; ++i) {
;       const int id = tid + 256 * i, row = id >> 3, ch = id & 7;
;       *reinterpret_cast<u32x4*>(sA + row * LDT + ch * 8) = xa[i];
;       *reinterpret_cast<u32x4*>(sB + row * LDT + ch * 8) = xb[i];
;     }
;   };
;   auto ldfrag = [&](int ks, bf16x8 (&af)[2], bf16x8 (&bfr)[2]) {
; #pragma unroll
;     for (int t = 0; t < 2; ++t) {
;       af[t] = ld16(sA + (wm * 64 + t * 32 + r) * LDT + ks * 16 + h2 * 8);
;       bfr[t] = ld16(sB + (wn * 64 + t * 32 + r) * LDT + ks * 16 + h2 * 8);
;     }
;   };
;   auto mm = [&](const bf16x8 (&af)[2], const bf16x8 (&bfr)[2]) {
; #pragma unroll
;     for (int mt = 0; mt < 2; ++mt)
; #pragma unroll
;       for (int nt = 0; nt < 2; ++nt) {
;         if (SWAP) acc[mt][nt] = MFMA32(bfr[nt], af[mt], acc[mt][nt]);
;         else acc[mt][nt] = MFMA32(af[mt], bfr[nt], acc[mt][nt]);
;       }
;   };
;   auto compute = [&]() {
;     bf16x8 a0[2], b0[2], a1[2], b1[2];
;     ldfrag(0, a0, b0);
;     ldfrag(1, a1, b1);
;     __builtin_amdgcn_sched_barrier(0);
;     mm(a0, b0);
;     __builtin_amdgcn_sched_barrier(0);
;     ldfrag(2, a0, b0);
;     __builtin_amdgcn_sched_barrier(0);
;     mm(a1, b1);
;     __builtin_amdgcn_sched_barrier(0);
;     ldfrag(3, a1, b1);
;     __builtin_amdgcn_sched_barrier(0);
;     mm(a0, b0);
;     mm(a1, b1);
;   };
;   gload(0, ra[0], rb[0]);
;   for (int kt = 0; kt < nk; ++kt) {
;     stage(ra[0], rb[0]);
;     __syncthreads();
;     if (kt + 1 < nk) gload(kt + 1, ra[0], rb[0]);
;     __builtin_amdgcn_sched_barrier(0);
;     compute();
;     __syncthreads();
;   }
.Lmy_p13_loop:
	s_waitcnt vmcnt(8)
	ds_write_b128 v119, v[202:205]
	ds_write_b128 v119, v[206:209] offset:18432
	ds_write_b128 v118, v[210:213]
	ds_write_b128 v118, v[214:217] offset:18432
	ds_write_b128 v117, v[218:221]
	ds_write_b128 v117, v[222:225] offset:18432
	ds_write_b128 v116, v[152:155]
	ds_write_b128 v116, v[160:163] offset:18432
	ds_read_b128 v[120:123], v174
	ds_read_b128 v[124:127], v174 offset:32
	ds_read_b128 v[128:131], v175 offset:18432
	ds_read_b128 v[132:135], v175 offset:18464
	ds_read_b128 v[136:139], v174 offset:4608
	ds_read_b128 v[140:143], v174 offset:4640
	ds_read_b128 v[144:147], v175 offset:23040
	ds_read_b128 v[148:151], v175 offset:23072
	s_waitcnt lgkmcnt(5)
	v_mfma_f32_32x32x16_bf16 v[50:65], v[128:131], v[120:123], v[50:65]
	global_load_dwordx4 v[202:205], v[98:99], off offset:128
	global_load_dwordx4 v[206:209], v[100:101], off offset:128
	global_load_dwordx4 v[210:213], v[102:103], off offset:128
	global_load_dwordx4 v[214:217], v[104:105], off offset:128
	global_load_dwordx4 v[218:221], v[106:107], off offset:128
	global_load_dwordx4 v[222:225], v[108:109], off offset:128
	global_load_dwordx4 v[152:155], v[110:111], off offset:128
	global_load_dwordx4 v[160:163], v[112:113], off offset:128
	v_lshl_add_u64 v[98:99], v[98:99], 0, s[30:31]
	v_lshl_add_u64 v[100:101], v[100:101], 0, s[30:31]
	v_lshl_add_u64 v[102:103], v[102:103], 0, s[30:31]
	v_lshl_add_u64 v[104:105], v[104:105], 0, s[30:31]
	v_lshl_add_u64 v[106:107], v[106:107], 0, s[30:31]
	v_lshl_add_u64 v[108:109], v[108:109], 0, s[30:31]
	v_lshl_add_u64 v[110:111], v[110:111], 0, s[30:31]
	v_lshl_add_u64 v[112:113], v[112:113], 0, s[30:31]
	s_waitcnt lgkmcnt(1)
	v_mfma_f32_32x32x16_bf16 v[34:49], v[144:147], v[120:123], v[34:49]
	v_mfma_f32_32x32x16_bf16 v[18:33], v[128:131], v[136:139], v[18:33]
	v_mfma_f32_32x32x16_bf16 v[2:17], v[144:147], v[136:139], v[2:17]
	ds_read_b128 v[120:123], v174 offset:64
	ds_read_b128 v[128:131], v174 offset:4672
	ds_read_b128 v[136:139], v175 offset:18496
	ds_read_b128 v[144:147], v175 offset:23104
	v_mfma_f32_32x32x16_bf16 v[50:65], v[132:135], v[124:127], v[50:65]
	s_waitcnt lgkmcnt(4)
	v_mfma_f32_32x32x16_bf16 v[34:49], v[148:151], v[124:127], v[34:49]
	v_mfma_f32_32x32x16_bf16 v[18:33], v[132:135], v[140:143], v[18:33]
	v_mfma_f32_32x32x16_bf16 v[2:17], v[148:151], v[140:143], v[2:17]
	ds_read_b128 v[124:127], v174 offset:96
	ds_read_b128 v[132:135], v174 offset:4704
	ds_read_b128 v[140:143], v175 offset:18528
	ds_read_b128 v[148:151], v175 offset:23136
	s_waitcnt lgkmcnt(5)
	v_mfma_f32_32x32x16_bf16 v[50:65], v[136:139], v[120:123], v[50:65]
	s_waitcnt lgkmcnt(0)
	s_barrier
	v_mfma_f32_32x32x16_bf16 v[34:49], v[144:147], v[120:123], v[34:49]
	v_mfma_f32_32x32x16_bf16 v[18:33], v[136:139], v[128:131], v[18:33]
	v_mfma_f32_32x32x16_bf16 v[2:17], v[144:147], v[128:131], v[2:17]
	v_mfma_f32_32x32x16_bf16 v[50:65], v[140:143], v[124:127], v[50:65]
	v_mfma_f32_32x32x16_bf16 v[34:49], v[148:151], v[124:127], v[34:49]
	v_mfma_f32_32x32x16_bf16 v[18:33], v[140:143], v[132:135], v[18:33]
	v_mfma_f32_32x32x16_bf16 v[2:17], v[148:151], v[132:135], v[2:17]
	s_waitcnt vmcnt(8)
	ds_write_b128 v170, v[94:97]
	ds_write_b128 v170, v[86:89] offset:18432
	ds_write_b128 v171, v[90:93]
	ds_write_b128 v171, v[78:81] offset:18432
	ds_write_b128 v172, v[82:85]
	ds_write_b128 v172, v[66:69] offset:18432
	ds_write_b128 v173, v[74:77]
	ds_write_b128 v173, v[70:73] offset:18432
	ds_read_b128 v[120:123], v114
	ds_read_b128 v[124:127], v114 offset:32
	ds_read_b128 v[128:131], v115 offset:18432
	ds_read_b128 v[132:135], v115 offset:18464
	ds_read_b128 v[136:139], v114 offset:4608
	ds_read_b128 v[140:143], v114 offset:4640
	ds_read_b128 v[144:147], v115 offset:23040
	ds_read_b128 v[148:151], v115 offset:23072
	s_waitcnt lgkmcnt(5)
	v_mfma_f32_32x32x16_bf16 v[50:65], v[128:131], v[120:123], v[50:65]
	global_load_dwordx4 v[94:97], v[98:99], off offset:128
	global_load_dwordx4 v[86:89], v[100:101], off offset:128
	global_load_dwordx4 v[90:93], v[102:103], off offset:128
	global_load_dwordx4 v[78:81], v[104:105], off offset:128
	global_load_dwordx4 v[82:85], v[106:107], off offset:128
	global_load_dwordx4 v[66:69], v[108:109], off offset:128
	global_load_dwordx4 v[74:77], v[110:111], off offset:128
	global_load_dwordx4 v[70:73], v[112:113], off offset:128
	v_lshl_add_u64 v[98:99], v[98:99], 0, s[30:31]
	v_lshl_add_u64 v[100:101], v[100:101], 0, s[30:31]
	v_lshl_add_u64 v[102:103], v[102:103], 0, s[30:31]
	v_lshl_add_u64 v[104:105], v[104:105], 0, s[30:31]
	v_lshl_add_u64 v[106:107], v[106:107], 0, s[30:31]
	v_lshl_add_u64 v[108:109], v[108:109], 0, s[30:31]
	v_lshl_add_u64 v[110:111], v[110:111], 0, s[30:31]
	v_lshl_add_u64 v[112:113], v[112:113], 0, s[30:31]
	s_waitcnt lgkmcnt(1)
	v_mfma_f32_32x32x16_bf16 v[34:49], v[144:147], v[120:123], v[34:49]
	v_mfma_f32_32x32x16_bf16 v[18:33], v[128:131], v[136:139], v[18:33]
	v_mfma_f32_32x32x16_bf16 v[2:17], v[144:147], v[136:139], v[2:17]
	ds_read_b128 v[120:123], v114 offset:64
	ds_read_b128 v[128:131], v114 offset:4672
	ds_read_b128 v[136:139], v115 offset:18496
	ds_read_b128 v[144:147], v115 offset:23104
	v_mfma_f32_32x32x16_bf16 v[50:65], v[132:135], v[124:127], v[50:65]
	s_waitcnt lgkmcnt(4)
	v_mfma_f32_32x32x16_bf16 v[34:49], v[148:151], v[124:127], v[34:49]
	v_mfma_f32_32x32x16_bf16 v[18:33], v[132:135], v[140:143], v[18:33]
	v_mfma_f32_32x32x16_bf16 v[2:17], v[148:151], v[140:143], v[2:17]
	ds_read_b128 v[124:127], v114 offset:96
	ds_read_b128 v[132:135], v114 offset:4704
	ds_read_b128 v[140:143], v115 offset:18528
	ds_read_b128 v[148:151], v115 offset:23136
	s_waitcnt lgkmcnt(5)
	v_mfma_f32_32x32x16_bf16 v[50:65], v[136:139], v[120:123], v[50:65]
	s_waitcnt lgkmcnt(0)
	s_barrier
; template <int AMODE, bool SWAP>
; DI void gemm_core(const u16* __restrict__ A, int lda, const u16* __restrict__ Bt, int ldb, int K, int m0, int n0, int acol,
;                   f32x16 (&acc)[2][2], u16* sA, u16* sB) {
;     ...
;   auto compute = [&]() {
;     bf16x8 a0[2], b0[2], a1[2], b1[2];
;     ldfrag(0, a0, b0);
;     ldfrag(1, a1, b1);
;     __builtin_amdgcn_sched_barrier(0);
;     mm(a0, b0);
;     __builtin_amdgcn_sched_barrier(0);
;     ldfrag(2, a0, b0);
;     __builtin_amdgcn_sched_barrier(0);
;     mm(a1, b1);
;     __builtin_amdgcn_sched_barrier(0);
;     ldfrag(3, a1, b1);
;     __builtin_amdgcn_sched_barrier(0);
;     mm(a0, b0);
;     mm(a1, b1);
;   };
;   gload(0, ra[0], rb[0]);
;   for (int kt = 0; kt < nk; ++kt) {
;     stage(ra[0], rb[0]);
;     __syncthreads();
;     if (kt + 1 < nk) gload(kt + 1, ra[0], rb[0]);
;     __builtin_amdgcn_sched_barrier(0);
;     compute();
;     __syncthreads();
;   }
	v_mfma_f32_32x32x16_bf16 v[34:49], v[144:147], v[120:123], v[34:49]
	v_mfma_f32_32x32x16_bf16 v[18:33], v[136:139], v[128:131], v[18:33]
	v_mfma_f32_32x32x16_bf16 v[2:17], v[144:147], v[128:131], v[2:17]
	v_mfma_f32_32x32x16_bf16 v[50:65], v[140:143], v[124:127], v[50:65]
	v_mfma_f32_32x32x16_bf16 v[34:49], v[148:151], v[124:127], v[34:49]
	v_mfma_f32_32x32x16_bf16 v[18:33], v[140:143], v[132:135], v[18:33]
	v_mfma_f32_32x32x16_bf16 v[2:17], v[148:151], v[132:135], v[2:17]
	s_add_i32 s100, s100, 1
	s_cmp_lt_u32 s100, 6
	s_cbranch_scc1 .Lmy_p13_loop
	s_waitcnt vmcnt(8)
	ds_write_b128 v119, v[202:205]
	ds_write_b128 v119, v[206:209] offset:18432
	ds_write_b128 v118, v[210:213]
	ds_write_b128 v118, v[214:217] offset:18432
	ds_write_b128 v117, v[218:221]
	ds_write_b128 v117, v[222:225] offset:18432
	ds_write_b128 v116, v[152:155]
	ds_write_b128 v116, v[160:163] offset:18432
	ds_read_b128 v[120:123], v174
	ds_read_b128 v[124:127], v174 offset:32
	ds_read_b128 v[128:131], v175 offset:18432
	ds_read_b128 v[132:135], v175 offset:18464
	ds_read_b128 v[136:139], v174 offset:4608
	ds_read_b128 v[140:143], v174 offset:4640
	ds_read_b128 v[144:147], v175 offset:23040
	ds_read_b128 v[148:151], v175 offset:23072
	s_waitcnt lgkmcnt(5)
	v_mfma_f32_32x32x16_bf16 v[50:65], v[128:131], v[120:123], v[50:65]
	global_load_dwordx4 v[202:205], v[98:99], off offset:128
	global_load_dwordx4 v[206:209], v[100:101], off offset:128
	global_load_dwordx4 v[210:213], v[102:103], off offset:128
	global_load_dwordx4 v[214:217], v[104:105], off offset:128
	global_load_dwordx4 v[218:221], v[106:107], off offset:128
	global_load_dwordx4 v[222:225], v[108:109], off offset:128
	global_load_dwordx4 v[152:155], v[110:111], off offset:128
	global_load_dwordx4 v[160:163], v[112:113], off offset:128
	v_lshl_add_u64 v[98:99], v[98:99], 0, s[30:31]
	v_lshl_add_u64 v[100:101], v[100:101], 0, s[30:31]
	v_lshl_add_u64 v[102:103], v[102:103], 0, s[30:31]
	v_lshl_add_u64 v[104:105], v[104:105], 0, s[30:31]
	v_lshl_add_u64 v[106:107], v[106:107], 0, s[30:31]
	v_lshl_add_u64 v[108:109], v[108:109], 0, s[30:31]
	v_lshl_add_u64 v[110:111], v[110:111], 0, s[30:31]
	v_lshl_add_u64 v[112:113], v[112:113], 0, s[30:31]
	s_waitcnt lgkmcnt(1)
	v_mfma_f32_32x32x16_bf16 v[34:49], v[144:147], v[120:123], v[34:49]
	v_mfma_f32_32x32x16_bf16 v[18:33], v[128:131], v[136:139], v[18:33]
	v_mfma_f32_32x32x16_bf16 v[2:17], v[144:147], v[136:139], v[2:17]
	ds_read_b128 v[120:123], v174 offset:64
	ds_read_b128 v[128:131], v174 offset:4672
	ds_read_b128 v[136:139], v175 offset:18496
	ds_read_b128 v[144:147], v175 offset:23104
	v_mfma_f32_32x32x16_bf16 v[50:65], v[132:135], v[124:127], v[50:65]
	s_waitcnt lgkmcnt(4)
	v_mfma_f32_32x32x16_bf16 v[34:49], v[148:151], v[124:127], v[34:49]
	v_mfma_f32_32x32x16_bf16 v[18:33], v[132:135], v[140:143], v[18:33]
	v_mfma_f32_32x32x16_bf16 v[2:17], v[148:151], v[140:143], v[2:17]
	ds_read_b128 v[124:127], v174 offset:96
	ds_read_b128 v[132:135], v174 offset:4704
	ds_read_b128 v[140:143], v175 offset:18528
	ds_read_b128 v[148:151], v175 offset:23136
	s_waitcnt lgkmcnt(5)
	v_mfma_f32_32x32x16_bf16 v[50:65], v[136:139], v[120:123], v[50:65]
	s_waitcnt lgkmcnt(0)
	s_barrier
	v_mfma_f32_32x32x16_bf16 v[34:49], v[144:147], v[120:123], v[34:49]
	v_mfma_f32_32x32x16_bf16 v[18:33], v[136:139], v[128:131], v[18:33]
	v_mfma_f32_32x32x16_bf16 v[2:17], v[144:147], v[128:131], v[2:17]
	v_mfma_f32_32x32x16_bf16 v[50:65], v[140:143], v[124:127], v[50:65]
	v_mfma_f32_32x32x16_bf16 v[34:49], v[148:151], v[124:127], v[34:49]
	v_mfma_f32_32x32x16_bf16 v[18:33], v[140:143], v[132:135], v[18:33]
	v_mfma_f32_32x32x16_bf16 v[2:17], v[148:151], v[132:135], v[2:17]
	s_waitcnt vmcnt(8)
	ds_write_b128 v170, v[94:97]
	ds_write_b128 v170, v[86:89] offset:18432
	ds_write_b128 v171, v[90:93]
	ds_write_b128 v171, v[78:81] offset:18432
	ds_write_b128 v172, v[82:85]
	ds_write_b128 v172, v[66:69] offset:18432
	ds_write_b128 v173, v[74:77]
	ds_write_b128 v173, v[70:73] offset:18432
	ds_read_b128 v[120:123], v114
	ds_read_b128 v[124:127], v114 offset:32
	ds_read_b128 v[128:131], v115 offset:18432
	ds_read_b128 v[132:135], v115 offset:18464
	ds_read_b128 v[136:139], v114 offset:4608
	ds_read_b128 v[140:143], v114 offset:4640
	ds_read_b128 v[144:147], v115 offset:23040
	ds_read_b128 v[148:151], v115 offset:23072
	s_waitcnt lgkmcnt(5)
	v_mfma_f32_32x32x16_bf16 v[50:65], v[128:131], v[120:123], v[50:65]
	s_waitcnt lgkmcnt(1)
	v_mfma_f32_32x32x16_bf16 v[34:49], v[144:147], v[120:123], v[34:49]
	v_mfma_f32_32x32x16_bf16 v[18:33], v[128:131], v[136:139], v[18:33]
	v_mfma_f32_32x32x16_bf16 v[2:17], v[144:147], v[136:139], v[2:17]
	ds_read_b128 v[120:123], v114 offset:64
	ds_read_b128 v[128:131], v114 offset:4672
	ds_read_b128 v[136:139], v115 offset:18496
	ds_read_b128 v[144:147], v115 offset:23104
	v_mfma_f32_32x32x16_bf16 v[50:65], v[132:135], v[124:127], v[50:65]
	s_waitcnt lgkmcnt(4)
	v_mfma_f32_32x32x16_bf16 v[34:49], v[148:151], v[124:127], v[34:49]
	v_mfma_f32_32x32x16_bf16 v[18:33], v[132:135], v[140:143], v[18:33]
	v_mfma_f32_32x32x16_bf16 v[2:17], v[148:151], v[140:143], v[2:17]
	ds_read_b128 v[124:127], v114 offset:96
	ds_read_b128 v[132:135], v114 offset:4704
	ds_read_b128 v[140:143], v115 offset:18528
	ds_read_b128 v[148:151], v115 offset:23136
	s_waitcnt lgkmcnt(5)
	v_mfma_f32_32x32x16_bf16 v[50:65], v[136:139], v[120:123], v[50:65]
	s_waitcnt lgkmcnt(0)
	s_barrier
; template <int AMODE, bool SWAP>
; DI void gemm_core(const u16* __restrict__ A, int lda, const u16* __restrict__ Bt, int ldb, int K, int m0, int n0, int acol,
;                   f32x16 (&acc)[2][2], u16* sA, u16* sB) {
;     ...
;   auto compute = [&]() {
;     bf16x8 a0[2], b0[2], a1[2], b1[2];
;     ldfrag(0, a0, b0);
;     ldfrag(1, a1, b1);
;     __builtin_amdgcn_sched_barrier(0);
;     mm(a0, b0);
;     __builtin_amdgcn_sched_barrier(0);
;     ldfrag(2, a0, b0);
;     __builtin_amdgcn_sched_barrier(0);
;     mm(a1, b1);
;     __builtin_amdgcn_sched_barrier(0);
;     ldfrag(3, a1, b1);
;     __builtin_amdgcn_sched_barrier(0);
;     mm(a0, b0);
;     mm(a1, b1);
;   };
;   gload(0, ra[0], rb[0]);
;   for (int kt = 0; kt < nk; ++kt) {
;     stage(ra[0], rb[0]);
;     __syncthreads();
;     if (kt + 1 < nk) gload(kt + 1, ra[0], rb[0]);
;     __builtin_amdgcn_sched_barrier(0);
;     compute();
;     __syncthreads();
; __global__ void __launch_bounds__(512, 2) mega(Params P) {
;     ...
;           const float* bgp = P.b_pg + L * DM;
;           EPI_LOOP_BEGIN EPI_SWAP_IDX
;             f32x4 bb = *reinterpret_cast<const f32x4*>(bgp + nb);
	v_mfma_f32_32x32x16_bf16 v[34:49], v[144:147], v[120:123], v[34:49]
	v_mfma_f32_32x32x16_bf16 v[18:33], v[136:139], v[128:131], v[18:33]
	v_mfma_f32_32x32x16_bf16 v[2:17], v[144:147], v[128:131], v[2:17]
	v_mfma_f32_32x32x16_bf16 v[50:65], v[140:143], v[124:127], v[50:65]
	v_mfma_f32_32x32x16_bf16 v[34:49], v[148:151], v[124:127], v[34:49]
	v_mfma_f32_32x32x16_bf16 v[18:33], v[140:143], v[132:135], v[18:33]
	v_mfma_f32_32x32x16_bf16 v[2:17], v[148:151], v[132:135], v[2:17]
	s_waitcnt vmcnt(0)
	ds_write_b128 v119, v[202:205]
	ds_write_b128 v119, v[206:209] offset:18432
	ds_write_b128 v118, v[210:213]
	ds_write_b128 v118, v[214:217] offset:18432
	ds_write_b128 v117, v[218:221]
	ds_write_b128 v117, v[222:225] offset:18432
	ds_write_b128 v116, v[152:155]
	ds_write_b128 v116, v[160:163] offset:18432
	ds_read_b128 v[120:123], v174
	ds_read_b128 v[124:127], v174 offset:32
	ds_read_b128 v[128:131], v175 offset:18432
	ds_read_b128 v[132:135], v175 offset:18464
	ds_read_b128 v[136:139], v174 offset:4608
	ds_read_b128 v[140:143], v174 offset:4640
	ds_read_b128 v[144:147], v175 offset:23040
	ds_read_b128 v[148:151], v175 offset:23072
	s_waitcnt lgkmcnt(5)
	v_mfma_f32_32x32x16_bf16 v[50:65], v[128:131], v[120:123], v[50:65]
	s_waitcnt lgkmcnt(1)
	v_mfma_f32_32x32x16_bf16 v[34:49], v[144:147], v[120:123], v[34:49]
	v_mfma_f32_32x32x16_bf16 v[18:33], v[128:131], v[136:139], v[18:33]
	v_mfma_f32_32x32x16_bf16 v[2:17], v[144:147], v[136:139], v[2:17]
	ds_read_b128 v[120:123], v174 offset:64
	ds_read_b128 v[128:131], v174 offset:4672
	ds_read_b128 v[136:139], v175 offset:18496
	ds_read_b128 v[144:147], v175 offset:23104
	v_mfma_f32_32x32x16_bf16 v[50:65], v[132:135], v[124:127], v[50:65]
	s_waitcnt lgkmcnt(4)
	v_mfma_f32_32x32x16_bf16 v[34:49], v[148:151], v[124:127], v[34:49]
	v_mfma_f32_32x32x16_bf16 v[18:33], v[132:135], v[140:143], v[18:33]
	v_mfma_f32_32x32x16_bf16 v[2:17], v[148:151], v[140:143], v[2:17]
	ds_read_b128 v[124:127], v174 offset:96
	ds_read_b128 v[132:135], v174 offset:4704
	ds_read_b128 v[140:143], v175 offset:18528
	ds_read_b128 v[148:151], v175 offset:23136
	s_waitcnt lgkmcnt(5)
	v_mfma_f32_32x32x16_bf16 v[50:65], v[136:139], v[120:123], v[50:65]
	s_waitcnt lgkmcnt(0)
	s_barrier
	v_mfma_f32_32x32x16_bf16 v[34:49], v[144:147], v[120:123], v[34:49]
	v_mfma_f32_32x32x16_bf16 v[18:33], v[136:139], v[128:131], v[18:33]
	v_mfma_f32_32x32x16_bf16 v[2:17], v[144:147], v[128:131], v[2:17]
	v_mfma_f32_32x32x16_bf16 v[50:65], v[140:143], v[124:127], v[50:65]
	v_mfma_f32_32x32x16_bf16 v[34:49], v[148:151], v[124:127], v[34:49]
	v_mfma_f32_32x32x16_bf16 v[18:33], v[140:143], v[132:135], v[18:33]
	v_mfma_f32_32x32x16_bf16 v[2:17], v[148:151], v[132:135], v[2:17]
	ds_read_b128 v[66:69], v114
	ds_read_b128 v[70:73], v114 offset:32
	ds_read_b128 v[74:77], v115 offset:18432
	ds_read_b128 v[78:81], v115 offset:18464
	ds_read_b128 v[82:85], v114 offset:4608
	ds_read_b128 v[86:89], v114 offset:4640
	ds_read_b128 v[90:93], v115 offset:23040
	ds_read_b128 v[94:97], v115 offset:23072
	s_waitcnt lgkmcnt(5)
	v_mfma_f32_32x32x16_bf16 v[50:65], v[74:77], v[66:69], v[50:65]
	s_waitcnt lgkmcnt(1)
	v_mfma_f32_32x32x16_bf16 v[34:49], v[90:93], v[66:69], v[34:49]
	v_mfma_f32_32x32x16_bf16 v[18:33], v[74:77], v[82:85], v[18:33]
	v_mfma_f32_32x32x16_bf16 v[2:17], v[90:93], v[82:85], v[2:17]
	ds_read_b128 v[66:69], v114 offset:64
	ds_read_b128 v[74:77], v114 offset:4672
	ds_read_b128 v[82:85], v115 offset:18496
	ds_read_b128 v[90:93], v115 offset:23104
	v_mfma_f32_32x32x16_bf16 v[50:65], v[78:81], v[70:73], v[50:65]
	s_waitcnt lgkmcnt(4)
	v_mfma_f32_32x32x16_bf16 v[34:49], v[94:97], v[70:73], v[34:49]
	v_mfma_f32_32x32x16_bf16 v[18:33], v[78:81], v[86:89], v[18:33]
	v_mfma_f32_32x32x16_bf16 v[2:17], v[94:97], v[86:89], v[2:17]
	ds_read_b128 v[70:73], v114 offset:96
	ds_read_b128 v[78:81], v114 offset:4704
	ds_read_b128 v[86:89], v115 offset:18528
	ds_read_b128 v[94:97], v115 offset:23136
	s_waitcnt lgkmcnt(5)
	v_mfma_f32_32x32x16_bf16 v[50:65], v[82:85], v[66:69], v[50:65]
	v_mov_b32_e32 v0, v159
	s_waitcnt lgkmcnt(0)
	s_barrier
	v_readlane_b32 s12, v252, 50
	v_lshrrev_b32_e32 v0, 3, v0
	v_mfma_f32_32x32x16_bf16 v[34:49], v[90:93], v[66:69], v[34:49]
	v_mov_b32_e32 v66, v159
	v_and_b32_e32 v0, 4, v0
	v_and_b32_e32 v66, 64, v66
	v_or3_b32 v66, v66, v0, s21
	v_ashrrev_i32_e32 v67, 31, v66
	v_readlane_b32 s13, v252, 51
	v_mfma_f32_32x32x16_bf16 v[50:65], v[86:89], v[70:73], v[50:65]
	v_mfma_f32_32x32x16_bf16 v[34:49], v[94:97], v[70:73], v[34:49]
	v_lshl_add_u64 v[70:71], v[66:67], 2, s[26:27]
	global_load_dwordx4 v[66:69], v[70:71], off
	global_load_dwordx4 v[202:205], v[70:71], off offset:32
	global_load_dwordx4 v[206:209], v[70:71], off offset:64
	global_load_dwordx4 v[210:213], v[70:71], off offset:96
	global_load_dwordx4 v[214:217], v[70:71], off offset:128
	global_load_dwordx4 v[218:221], v[70:71], off offset:160
	global_load_dwordx4 v[222:225], v[70:71], off offset:192
	global_load_dwordx4 v[152:155], v[70:71], off offset:224
	s_waitcnt vmcnt(0)
; DI float sigmoidf_(float x) { return 1.f / (1.f + __expf(-x)); }
; __global__ void __launch_bounds__(512, 2) mega(Params P) {
;     ...
;           const float* bgp = P.b_pg + L * DM;
;           EPI_LOOP_BEGIN EPI_SWAP_IDX
;             f32x4 bb = *reinterpret_cast<const f32x4*>(bgp + nb);
;             (void)m;
;             gatepk[mt][nt][2 * g] = pack2(sigmoidf_(acc[mt][nt][4 * g] + bb[0]), sigmoidf_(acc[mt][nt][4 * g + 1] + bb[1]));
;             gatepk[mt][nt][2 * g + 1] = pack2(sigmoidf_(acc[mt][nt][4 * g + 2] + bb[2]), sigmoidf_(acc[mt][nt][4 * g + 3] + bb[3]));
;           EPI_LOOP_END
	s_nop 7
	v_add_f32_e32 v0, v66, v50
	v_mul_f32_e32 v0, 0xbfb8aa3b, v0
	v_exp_f32_e32 v50, v0
	v_add_f32_e32 v0, v67, v51
	v_mul_f32_e32 v0, 0xbfb8aa3b, v0
	v_exp_f32_e32 v51, v0
	v_mfma_f32_32x32x16_bf16 v[18:33], v[82:85], v[74:77], v[18:33]
	v_add_f32_e64 v50, v50, 1.0
	v_add_f32_e64 v51, v51, 1.0
	v_div_scale_f32 v0, s[10:11], v51, v51, 1.0
	v_rcp_f32_e32 v72, v0
	v_mfma_f32_32x32x16_bf16 v[2:17], v[90:93], v[74:77], v[2:17]
	v_fma_f32 v73, -v0, v72, 1.0
	v_fmac_f32_e32 v72, v73, v72
	v_div_scale_f32 v73, vcc, 1.0, v51, 1.0
	v_mul_f32_e32 v74, v73, v72
	v_fma_f32 v75, -v0, v74, v73
	v_fmac_f32_e32 v74, v75, v72
	v_fma_f32 v0, -v0, v74, v73
	v_div_fmas_f32 v0, v0, v72, v74
	v_div_fixup_f32 v0, v0, v51, 1.0
	v_div_scale_f32 v51, s[10:11], v50, v50, 1.0
	v_rcp_f32_e32 v72, v51
	v_mfma_f32_32x32x16_bf16 v[18:33], v[86:89], v[78:81], v[18:33]
	v_fma_f32 v73, -v51, v72, 1.0
	v_fmac_f32_e32 v72, v73, v72
	v_div_scale_f32 v73, vcc, 1.0, v50, 1.0
	v_mul_f32_e32 v74, v73, v72
	v_fma_f32 v75, -v51, v74, v73
	v_fmac_f32_e32 v74, v75, v72
	v_fma_f32 v51, -v51, v74, v73
	v_div_fmas_f32 v51, v51, v72, v74
	v_div_fixup_f32 v50, v51, v50, 1.0
	v_cvt_pk_bf16_f32 v114, v50, v0
	v_add_f32_e32 v0, v68, v52
	v_mul_f32_e32 v0, 0xbfb8aa3b, v0
	v_exp_f32_e32 v50, v0
	v_add_f32_e32 v0, v69, v53
	v_mul_f32_e32 v0, 0xbfb8aa3b, v0
	v_exp_f32_e32 v51, v0
	v_mfma_f32_32x32x16_bf16 v[2:17], v[94:97], v[78:81], v[2:17]
	v_add_f32_e64 v50, v50, 1.0
	v_add_f32_e64 v51, v51, 1.0
	v_div_scale_f32 v0, s[10:11], v51, v51, 1.0
	v_rcp_f32_e32 v52, v0
	s_nop 0
	v_fma_f32 v53, -v0, v52, 1.0
	v_fmac_f32_e32 v52, v53, v52
	v_div_scale_f32 v53, vcc, 1.0, v51, 1.0
	v_mul_f32_e32 v72, v53, v52
	v_fma_f32 v73, -v0, v72, v53
	v_fmac_f32_e32 v72, v73, v52
	v_fma_f32 v0, -v0, v72, v53
	v_div_fmas_f32 v0, v0, v52, v72
	v_div_fixup_f32 v0, v0, v51, 1.0
	v_div_scale_f32 v51, s[10:11], v50, v50, 1.0
	v_rcp_f32_e32 v52, v51
	s_nop 0
	v_fma_f32 v53, -v51, v52, 1.0
	v_fmac_f32_e32 v52, v53, v52
	v_div_scale_f32 v53, vcc, 1.0, v50, 1.0
	v_mul_f32_e32 v72, v53, v52
	v_fma_f32 v73, -v51, v72, v53
	v_fmac_f32_e32 v72, v73, v52
	v_fma_f32 v51, -v51, v72, v53
	v_div_fmas_f32 v51, v51, v52, v72
	v_div_fixup_f32 v50, v51, v50, 1.0
	v_cvt_pk_bf16_f32 v115, v50, v0
	v_mov_b64_e32 v[50:51], v[202:203]
	v_mov_b64_e32 v[52:53], v[204:205]
	v_add_f32_e32 v0, v50, v54
	v_mul_f32_e32 v0, 0xbfb8aa3b, v0
	v_exp_f32_e32 v54, v0
	v_add_f32_e32 v0, v51, v55
	v_mul_f32_e32 v0, 0xbfb8aa3b, v0
	v_exp_f32_e32 v55, v0
	s_nop 0
	v_pk_add_f32 v[54:55], v[54:55], 1.0 op_sel_hi:[1,0]
	s_nop 0
	v_div_scale_f32 v0, s[10:11], v55, v55, 1.0
	v_rcp_f32_e32 v72, v0
	s_nop 0
	v_fma_f32 v73, -v0, v72, 1.0
	v_fmac_f32_e32 v72, v73, v72
	v_div_scale_f32 v73, vcc, 1.0, v55, 1.0
	v_mul_f32_e32 v74, v73, v72
	v_fma_f32 v75, -v0, v74, v73
	v_fmac_f32_e32 v74, v75, v72
	v_fma_f32 v0, -v0, v74, v73
	v_div_fmas_f32 v0, v0, v72, v74
	v_div_fixup_f32 v0, v0, v55, 1.0
	v_div_scale_f32 v55, s[10:11], v54, v54, 1.0
	v_rcp_f32_e32 v72, v55
	s_nop 0
	v_fma_f32 v73, -v55, v72, 1.0
	v_fmac_f32_e32 v72, v73, v72
	v_div_scale_f32 v73, vcc, 1.0, v54, 1.0
	v_mul_f32_e32 v74, v73, v72
	v_fma_f32 v75, -v55, v74, v73
	v_fmac_f32_e32 v74, v75, v72
	v_fma_f32 v55, -v55, v74, v73
	v_div_fmas_f32 v55, v55, v72, v74
	v_div_fixup_f32 v54, v55, v54, 1.0
	v_cvt_pk_bf16_f32 v116, v54, v0
	v_add_f32_e32 v0, v52, v56
	v_mul_f32_e32 v0, 0xbfb8aa3b, v0
	v_exp_f32_e32 v54, v0
	v_add_f32_e32 v0, v53, v57
	v_mul_f32_e32 v0, 0xbfb8aa3b, v0
	v_exp_f32_e32 v55, v0
	s_nop 0
	v_pk_add_f32 v[54:55], v[54:55], 1.0 op_sel_hi:[1,0]
	s_nop 0
	v_div_scale_f32 v0, s[10:11], v55, v55, 1.0
	v_rcp_f32_e32 v56, v0
	s_nop 0
	v_fma_f32 v57, -v0, v56, 1.0
	v_fmac_f32_e32 v56, v57, v56
	v_div_scale_f32 v57, vcc, 1.0, v55, 1.0
	v_mul_f32_e32 v72, v57, v56
	v_fma_f32 v73, -v0, v72, v57
	v_fmac_f32_e32 v72, v73, v56
	v_fma_f32 v0, -v0, v72, v57
	v_div_fmas_f32 v0, v0, v56, v72
	v_div_fixup_f32 v0, v0, v55, 1.0
	v_div_scale_f32 v55, s[10:11], v54, v54, 1.0
	v_rcp_f32_e32 v56, v55
	s_nop 0
	v_fma_f32 v57, -v55, v56, 1.0
	v_fmac_f32_e32 v56, v57, v56
	v_div_scale_f32 v57, vcc, 1.0, v54, 1.0
	v_mul_f32_e32 v72, v57, v56
	v_fma_f32 v73, -v55, v72, v57
	v_fmac_f32_e32 v72, v73, v56
	v_fma_f32 v55, -v55, v72, v57
	v_div_fmas_f32 v55, v55, v56, v72
	v_div_fixup_f32 v54, v55, v54, 1.0
	v_cvt_pk_bf16_f32 v117, v54, v0
	v_mov_b64_e32 v[54:55], v[206:207]
	v_mov_b64_e32 v[56:57], v[208:209]
	v_add_f32_e32 v0, v54, v58
	v_mul_f32_e32 v0, 0xbfb8aa3b, v0
	v_exp_f32_e32 v58, v0
	v_add_f32_e32 v0, v55, v59
	v_mul_f32_e32 v0, 0xbfb8aa3b, v0
	v_exp_f32_e32 v59, v0
	s_nop 0
	v_pk_add_f32 v[58:59], v[58:59], 1.0 op_sel_hi:[1,0]
	s_nop 0
	v_div_scale_f32 v0, s[10:11], v59, v59, 1.0
	v_rcp_f32_e32 v72, v0
	s_nop 0
	v_fma_f32 v73, -v0, v72, 1.0
	v_fmac_f32_e32 v72, v73, v72
	v_div_scale_f32 v73, vcc, 1.0, v59, 1.0
	v_mul_f32_e32 v74, v73, v72
	v_fma_f32 v75, -v0, v74, v73
	v_fmac_f32_e32 v74, v75, v72
	v_fma_f32 v0, -v0, v74, v73
	v_div_fmas_f32 v0, v0, v72, v74
	v_div_fixup_f32 v0, v0, v59, 1.0
	v_div_scale_f32 v59, s[10:11], v58, v58, 1.0
	v_rcp_f32_e32 v72, v59
	s_nop 0
	v_fma_f32 v73, -v59, v72, 1.0
	v_fmac_f32_e32 v72, v73, v72
	v_div_scale_f32 v73, vcc, 1.0, v58, 1.0
	v_mul_f32_e32 v74, v73, v72
	v_fma_f32 v75, -v59, v74, v73
	v_fmac_f32_e32 v74, v75, v72
	v_fma_f32 v59, -v59, v74, v73
	v_div_fmas_f32 v59, v59, v72, v74
	v_div_fixup_f32 v58, v59, v58, 1.0
	v_cvt_pk_bf16_f32 v118, v58, v0
	v_add_f32_e32 v0, v56, v60
	v_mul_f32_e32 v0, 0xbfb8aa3b, v0
	v_exp_f32_e32 v58, v0
	v_add_f32_e32 v0, v57, v61
	v_mul_f32_e32 v0, 0xbfb8aa3b, v0
	v_exp_f32_e32 v59, v0
	s_nop 0
	v_pk_add_f32 v[58:59], v[58:59], 1.0 op_sel_hi:[1,0]
; DI float sigmoidf_(float x) { return 1.f / (1.f + __expf(-x)); }
; __global__ void __launch_bounds__(512, 2) mega(Params P) {
;     ...
;           const float* bgp = P.b_pg + L * DM;
;           EPI_LOOP_BEGIN EPI_SWAP_IDX
;             f32x4 bb = *reinterpret_cast<const f32x4*>(bgp + nb);
;             (void)m;
;             gatepk[mt][nt][2 * g] = pack2(sigmoidf_(acc[mt][nt][4 * g] + bb[0]), sigmoidf_(acc[mt][nt][4 * g + 1] + bb[1]));
;             gatepk[mt][nt][2 * g + 1] = pack2(sigmoidf_(acc[mt][nt][4 * g + 2] + bb[2]), sigmoidf_(acc[mt][nt][4 * g + 3] + bb[3]));
;           EPI_LOOP_END
	s_nop 0
	v_div_scale_f32 v0, s[10:11], v59, v59, 1.0
	v_rcp_f32_e32 v60, v0
	s_nop 0
	v_fma_f32 v61, -v0, v60, 1.0
	v_fmac_f32_e32 v60, v61, v60
	v_div_scale_f32 v61, vcc, 1.0, v59, 1.0
	v_mul_f32_e32 v72, v61, v60
	v_fma_f32 v73, -v0, v72, v61
	v_fmac_f32_e32 v72, v73, v60
	v_fma_f32 v0, -v0, v72, v61
	v_div_fmas_f32 v0, v0, v60, v72
	v_div_fixup_f32 v0, v0, v59, 1.0
	v_div_scale_f32 v59, s[10:11], v58, v58, 1.0
	v_rcp_f32_e32 v60, v59
	s_nop 0
	v_fma_f32 v61, -v59, v60, 1.0
	v_fmac_f32_e32 v60, v61, v60
	v_div_scale_f32 v61, vcc, 1.0, v58, 1.0
	v_mul_f32_e32 v72, v61, v60
	v_fma_f32 v73, -v59, v72, v61
	v_fmac_f32_e32 v72, v73, v60
	v_fma_f32 v59, -v59, v72, v61
	v_div_fmas_f32 v59, v59, v60, v72
	v_div_fixup_f32 v58, v59, v58, 1.0
	v_cvt_pk_bf16_f32 v119, v58, v0
	v_mov_b64_e32 v[58:59], v[210:211]
	v_mov_b64_e32 v[60:61], v[212:213]
	v_add_f32_e32 v0, v58, v62
	v_mul_f32_e32 v0, 0xbfb8aa3b, v0
	v_exp_f32_e32 v62, v0
	v_add_f32_e32 v0, v59, v63
	v_mul_f32_e32 v0, 0xbfb8aa3b, v0
	v_exp_f32_e32 v63, v0
	s_nop 0
	v_pk_add_f32 v[62:63], v[62:63], 1.0 op_sel_hi:[1,0]
	s_nop 0
	v_div_scale_f32 v0, s[10:11], v63, v63, 1.0
	v_rcp_f32_e32 v72, v0
	s_nop 0
	v_fma_f32 v73, -v0, v72, 1.0
	v_fmac_f32_e32 v72, v73, v72
	v_div_scale_f32 v73, vcc, 1.0, v63, 1.0
	v_mul_f32_e32 v74, v73, v72
	v_fma_f32 v75, -v0, v74, v73
	v_fmac_f32_e32 v74, v75, v72
	v_fma_f32 v0, -v0, v74, v73
	v_div_fmas_f32 v0, v0, v72, v74
	v_div_fixup_f32 v0, v0, v63, 1.0
	v_div_scale_f32 v63, s[10:11], v62, v62, 1.0
	v_rcp_f32_e32 v72, v63
	s_nop 0
	v_fma_f32 v73, -v63, v72, 1.0
	v_fmac_f32_e32 v72, v73, v72
	v_div_scale_f32 v73, vcc, 1.0, v62, 1.0
	v_mul_f32_e32 v74, v73, v72
	v_fma_f32 v75, -v63, v74, v73
	v_fmac_f32_e32 v74, v75, v72
	v_fma_f32 v63, -v63, v74, v73
	v_div_fmas_f32 v63, v63, v72, v74
	v_div_fixup_f32 v62, v63, v62, 1.0
	v_cvt_pk_bf16_f32 v120, v62, v0
	v_add_f32_e32 v0, v60, v64
	v_mul_f32_e32 v0, 0xbfb8aa3b, v0
	v_exp_f32_e32 v62, v0
	v_add_f32_e32 v0, v61, v65
	v_mul_f32_e32 v0, 0xbfb8aa3b, v0
	v_exp_f32_e32 v63, v0
	s_nop 0
	v_pk_add_f32 v[62:63], v[62:63], 1.0 op_sel_hi:[1,0]
	s_nop 0
	v_div_scale_f32 v0, s[10:11], v63, v63, 1.0
	v_rcp_f32_e32 v64, v0
	s_nop 0
	v_fma_f32 v65, -v0, v64, 1.0
	v_fmac_f32_e32 v64, v65, v64
	v_div_scale_f32 v65, vcc, 1.0, v63, 1.0
	v_mul_f32_e32 v72, v65, v64
	v_fma_f32 v73, -v0, v72, v65
	v_fmac_f32_e32 v72, v73, v64
	v_fma_f32 v0, -v0, v72, v65
	v_div_fmas_f32 v0, v0, v64, v72
	v_div_fixup_f32 v0, v0, v63, 1.0
	v_div_scale_f32 v63, s[10:11], v62, v62, 1.0
	v_rcp_f32_e32 v64, v63
	s_nop 0
	v_fma_f32 v65, -v63, v64, 1.0
	v_fmac_f32_e32 v64, v65, v64
	v_div_scale_f32 v65, vcc, 1.0, v62, 1.0
	v_mul_f32_e32 v72, v65, v64
	v_fma_f32 v73, -v63, v72, v65
	v_fmac_f32_e32 v72, v73, v64
	v_fma_f32 v63, -v63, v72, v65
	v_div_fmas_f32 v63, v63, v64, v72
	v_div_fixup_f32 v62, v63, v62, 1.0
	v_cvt_pk_bf16_f32 v121, v62, v0
	v_mov_b64_e32 v[62:63], v[214:215]
	v_mov_b64_e32 v[64:65], v[216:217]
	v_add_f32_e32 v0, v62, v34
	v_mul_f32_e32 v0, 0xbfb8aa3b, v0
	v_exp_f32_e32 v34, v0
	v_add_f32_e32 v0, v63, v35
	v_mul_f32_e32 v0, 0xbfb8aa3b, v0
	v_exp_f32_e32 v35, v0
	s_nop 0
	v_pk_add_f32 v[34:35], v[34:35], 1.0 op_sel_hi:[1,0]
	s_nop 0
	v_div_scale_f32 v0, s[10:11], v35, v35, 1.0
	v_rcp_f32_e32 v72, v0
	s_nop 0
	v_fma_f32 v73, -v0, v72, 1.0
	v_fmac_f32_e32 v72, v73, v72
	v_div_scale_f32 v73, vcc, 1.0, v35, 1.0
	v_mul_f32_e32 v74, v73, v72
	v_fma_f32 v75, -v0, v74, v73
	v_fmac_f32_e32 v74, v75, v72
	v_fma_f32 v0, -v0, v74, v73
	v_div_fmas_f32 v0, v0, v72, v74
	v_div_fixup_f32 v0, v0, v35, 1.0
	v_div_scale_f32 v35, s[10:11], v34, v34, 1.0
	v_rcp_f32_e32 v72, v35
	s_nop 0
	v_fma_f32 v73, -v35, v72, 1.0
	v_fmac_f32_e32 v72, v73, v72
	v_div_scale_f32 v73, vcc, 1.0, v34, 1.0
	v_mul_f32_e32 v74, v73, v72
	v_fma_f32 v75, -v35, v74, v73
	v_fmac_f32_e32 v74, v75, v72
	v_fma_f32 v35, -v35, v74, v73
	v_div_fmas_f32 v35, v35, v72, v74
	v_div_fixup_f32 v34, v35, v34, 1.0
	v_cvt_pk_bf16_f32 v122, v34, v0
	v_add_f32_e32 v0, v64, v36
	v_mul_f32_e32 v0, 0xbfb8aa3b, v0
	v_exp_f32_e32 v34, v0
	v_add_f32_e32 v0, v65, v37
	v_mul_f32_e32 v0, 0xbfb8aa3b, v0
	v_exp_f32_e32 v35, v0
	s_nop 0
	v_pk_add_f32 v[34:35], v[34:35], 1.0 op_sel_hi:[1,0]
	s_nop 0
	v_div_scale_f32 v0, s[10:11], v35, v35, 1.0
	v_rcp_f32_e32 v36, v0
	s_nop 0
	v_fma_f32 v37, -v0, v36, 1.0
	v_fmac_f32_e32 v36, v37, v36
	v_div_scale_f32 v37, vcc, 1.0, v35, 1.0
	v_mul_f32_e32 v72, v37, v36
	v_fma_f32 v73, -v0, v72, v37
	v_fmac_f32_e32 v72, v73, v36
	v_fma_f32 v0, -v0, v72, v37
	v_div_fmas_f32 v0, v0, v36, v72
	v_div_fixup_f32 v0, v0, v35, 1.0
	v_div_scale_f32 v35, s[10:11], v34, v34, 1.0
	v_rcp_f32_e32 v36, v35
	s_nop 0
	v_fma_f32 v37, -v35, v36, 1.0
	v_fmac_f32_e32 v36, v37, v36
	v_div_scale_f32 v37, vcc, 1.0, v34, 1.0
	v_mul_f32_e32 v72, v37, v36
	v_fma_f32 v73, -v35, v72, v37
	v_fmac_f32_e32 v72, v73, v36
	v_fma_f32 v35, -v35, v72, v37
	v_div_fmas_f32 v35, v35, v36, v72
	v_div_fixup_f32 v34, v35, v34, 1.0
	v_cvt_pk_bf16_f32 v123, v34, v0
	v_mov_b64_e32 v[34:35], v[218:219]
	v_mov_b64_e32 v[36:37], v[220:221]
	v_add_f32_e32 v0, v34, v38
	v_mul_f32_e32 v0, 0xbfb8aa3b, v0
	v_exp_f32_e32 v38, v0
	v_add_f32_e32 v0, v35, v39
	v_mul_f32_e32 v0, 0xbfb8aa3b, v0
	v_exp_f32_e32 v39, v0
	s_nop 0
	v_pk_add_f32 v[38:39], v[38:39], 1.0 op_sel_hi:[1,0]
	s_nop 0
	v_div_scale_f32 v0, s[10:11], v39, v39, 1.0
	v_rcp_f32_e32 v72, v0
	s_nop 0
	v_fma_f32 v73, -v0, v72, 1.0
	v_fmac_f32_e32 v72, v73, v72
	v_div_scale_f32 v73, vcc, 1.0, v39, 1.0
	v_mul_f32_e32 v74, v73, v72
	v_fma_f32 v75, -v0, v74, v73
	v_fmac_f32_e32 v74, v75, v72
	v_fma_f32 v0, -v0, v74, v73
	v_div_fmas_f32 v0, v0, v72, v74
	v_div_fixup_f32 v0, v0, v39, 1.0
; DI float sigmoidf_(float x) { return 1.f / (1.f + __expf(-x)); }
; __global__ void __launch_bounds__(512, 2) mega(Params P) {
;     ...
;           const float* bgp = P.b_pg + L * DM;
;           EPI_LOOP_BEGIN EPI_SWAP_IDX
;             f32x4 bb = *reinterpret_cast<const f32x4*>(bgp + nb);
;             (void)m;
;             gatepk[mt][nt][2 * g] = pack2(sigmoidf_(acc[mt][nt][4 * g] + bb[0]), sigmoidf_(acc[mt][nt][4 * g + 1] + bb[1]));
;             gatepk[mt][nt][2 * g + 1] = pack2(sigmoidf_(acc[mt][nt][4 * g + 2] + bb[2]), sigmoidf_(acc[mt][nt][4 * g + 3] + bb[3]));
;           EPI_LOOP_END
	v_div_scale_f32 v39, s[10:11], v38, v38, 1.0
	v_rcp_f32_e32 v72, v39
	s_nop 0
	v_fma_f32 v73, -v39, v72, 1.0
	v_fmac_f32_e32 v72, v73, v72
	v_div_scale_f32 v73, vcc, 1.0, v38, 1.0
	v_mul_f32_e32 v74, v73, v72
	v_fma_f32 v75, -v39, v74, v73
	v_fmac_f32_e32 v74, v75, v72
	v_fma_f32 v39, -v39, v74, v73
	v_div_fmas_f32 v39, v39, v72, v74
	v_div_fixup_f32 v38, v39, v38, 1.0
	v_cvt_pk_bf16_f32 v124, v38, v0
	v_add_f32_e32 v0, v36, v40
	v_mul_f32_e32 v0, 0xbfb8aa3b, v0
	v_exp_f32_e32 v38, v0
	v_add_f32_e32 v0, v37, v41
	v_mul_f32_e32 v0, 0xbfb8aa3b, v0
	v_exp_f32_e32 v39, v0
	s_nop 0
	v_pk_add_f32 v[38:39], v[38:39], 1.0 op_sel_hi:[1,0]
	s_nop 0
	v_div_scale_f32 v0, s[10:11], v39, v39, 1.0
	v_rcp_f32_e32 v40, v0
	s_nop 0
	v_fma_f32 v41, -v0, v40, 1.0
	v_fmac_f32_e32 v40, v41, v40
	v_div_scale_f32 v41, vcc, 1.0, v39, 1.0
	v_mul_f32_e32 v72, v41, v40
	v_fma_f32 v73, -v0, v72, v41
	v_fmac_f32_e32 v72, v73, v40
	v_fma_f32 v0, -v0, v72, v41
	v_div_fmas_f32 v0, v0, v40, v72
	v_div_fixup_f32 v0, v0, v39, 1.0
	v_div_scale_f32 v39, s[10:11], v38, v38, 1.0
	v_rcp_f32_e32 v40, v39
	s_nop 0
	v_fma_f32 v41, -v39, v40, 1.0
	v_fmac_f32_e32 v40, v41, v40
	v_div_scale_f32 v41, vcc, 1.0, v38, 1.0
	v_mul_f32_e32 v72, v41, v40
	v_fma_f32 v73, -v39, v72, v41
	v_fmac_f32_e32 v72, v73, v40
	v_fma_f32 v39, -v39, v72, v41
	v_div_fmas_f32 v39, v39, v40, v72
	v_div_fixup_f32 v38, v39, v38, 1.0
	v_cvt_pk_bf16_f32 v125, v38, v0
	v_mov_b64_e32 v[38:39], v[222:223]
	v_mov_b64_e32 v[40:41], v[224:225]
	v_add_f32_e32 v0, v38, v42
	v_mul_f32_e32 v0, 0xbfb8aa3b, v0
	v_exp_f32_e32 v42, v0
	v_add_f32_e32 v0, v39, v43
	v_mul_f32_e32 v0, 0xbfb8aa3b, v0
	v_exp_f32_e32 v43, v0
	s_nop 0
	v_pk_add_f32 v[42:43], v[42:43], 1.0 op_sel_hi:[1,0]
	s_nop 0
	v_div_scale_f32 v0, s[10:11], v43, v43, 1.0
	v_rcp_f32_e32 v72, v0
	s_nop 0
	v_fma_f32 v73, -v0, v72, 1.0
	v_fmac_f32_e32 v72, v73, v72
	v_div_scale_f32 v73, vcc, 1.0, v43, 1.0
	v_mul_f32_e32 v74, v73, v72
	v_fma_f32 v75, -v0, v74, v73
	v_fmac_f32_e32 v74, v75, v72
	v_fma_f32 v0, -v0, v74, v73
	v_div_fmas_f32 v0, v0, v72, v74
	v_div_fixup_f32 v0, v0, v43, 1.0
	v_div_scale_f32 v43, s[10:11], v42, v42, 1.0
	v_rcp_f32_e32 v72, v43
	s_nop 0
	v_fma_f32 v73, -v43, v72, 1.0
	v_fmac_f32_e32 v72, v73, v72
	v_div_scale_f32 v73, vcc, 1.0, v42, 1.0
	v_mul_f32_e32 v74, v73, v72
	v_fma_f32 v75, -v43, v74, v73
	v_fmac_f32_e32 v74, v75, v72
	v_fma_f32 v43, -v43, v74, v73
	v_div_fmas_f32 v43, v43, v72, v74
	v_div_fixup_f32 v42, v43, v42, 1.0
	v_cvt_pk_bf16_f32 v126, v42, v0
	v_add_f32_e32 v0, v40, v44
	v_mul_f32_e32 v0, 0xbfb8aa3b, v0
	v_exp_f32_e32 v42, v0
	v_add_f32_e32 v0, v41, v45
	v_mul_f32_e32 v0, 0xbfb8aa3b, v0
	v_exp_f32_e32 v43, v0
	s_nop 0
	v_pk_add_f32 v[42:43], v[42:43], 1.0 op_sel_hi:[1,0]
	s_nop 0
	v_div_scale_f32 v0, s[10:11], v43, v43, 1.0
	v_rcp_f32_e32 v44, v0
	s_nop 0
	v_fma_f32 v45, -v0, v44, 1.0
	v_fmac_f32_e32 v44, v45, v44
	v_div_scale_f32 v45, vcc, 1.0, v43, 1.0
	v_mul_f32_e32 v72, v45, v44
	v_fma_f32 v73, -v0, v72, v45
	v_fmac_f32_e32 v72, v73, v44
	v_fma_f32 v0, -v0, v72, v45
	v_div_fmas_f32 v0, v0, v44, v72
	v_div_fixup_f32 v0, v0, v43, 1.0
	v_div_scale_f32 v43, s[10:11], v42, v42, 1.0
	v_rcp_f32_e32 v44, v43
	s_nop 0
	v_fma_f32 v45, -v43, v44, 1.0
	v_fmac_f32_e32 v44, v45, v44
	v_div_scale_f32 v45, vcc, 1.0, v42, 1.0
	v_mul_f32_e32 v72, v45, v44
	v_fma_f32 v73, -v43, v72, v45
	v_fmac_f32_e32 v72, v73, v44
	v_fma_f32 v43, -v43, v72, v45
	v_div_fmas_f32 v43, v43, v44, v72
	v_div_fixup_f32 v42, v43, v42, 1.0
	v_cvt_pk_bf16_f32 v127, v42, v0
	v_mov_b64_e32 v[42:43], v[152:153]
	v_mov_b64_e32 v[44:45], v[154:155]
	v_add_f32_e32 v0, v42, v46
	v_mul_f32_e32 v0, 0xbfb8aa3b, v0
	v_exp_f32_e32 v46, v0
	v_add_f32_e32 v0, v43, v47
	v_mul_f32_e32 v0, 0xbfb8aa3b, v0
	v_exp_f32_e32 v47, v0
	s_nop 0
	v_pk_add_f32 v[46:47], v[46:47], 1.0 op_sel_hi:[1,0]
	s_nop 0
	v_div_scale_f32 v0, s[10:11], v47, v47, 1.0
	v_rcp_f32_e32 v70, v0
	s_nop 0
	v_fma_f32 v71, -v0, v70, 1.0
	v_fmac_f32_e32 v70, v71, v70
	v_div_scale_f32 v71, vcc, 1.0, v47, 1.0
	v_mul_f32_e32 v72, v71, v70
	v_fma_f32 v73, -v0, v72, v71
	v_fmac_f32_e32 v72, v73, v70
	v_fma_f32 v0, -v0, v72, v71
	v_div_fmas_f32 v0, v0, v70, v72
	v_div_fixup_f32 v0, v0, v47, 1.0
	v_div_scale_f32 v47, s[10:11], v46, v46, 1.0
	v_rcp_f32_e32 v70, v47
	s_nop 0
	v_fma_f32 v71, -v47, v70, 1.0
	v_fmac_f32_e32 v70, v71, v70
	v_div_scale_f32 v71, vcc, 1.0, v46, 1.0
	v_mul_f32_e32 v72, v71, v70
	v_fma_f32 v73, -v47, v72, v71
	v_fmac_f32_e32 v72, v73, v70
	v_fma_f32 v47, -v47, v72, v71
	v_div_fmas_f32 v47, v47, v70, v72
	v_div_fixup_f32 v46, v47, v46, 1.0
	v_cvt_pk_bf16_f32 v128, v46, v0
	v_add_f32_e32 v0, v44, v48
	v_mul_f32_e32 v0, 0xbfb8aa3b, v0
	v_exp_f32_e32 v46, v0
	v_add_f32_e32 v0, v45, v49
	v_mul_f32_e32 v0, 0xbfb8aa3b, v0
	v_exp_f32_e32 v47, v0
	s_nop 0
	v_pk_add_f32 v[46:47], v[46:47], 1.0 op_sel_hi:[1,0]
	s_nop 0
	v_div_scale_f32 v0, s[10:11], v47, v47, 1.0
	v_rcp_f32_e32 v48, v0
	s_nop 0
	v_fma_f32 v49, -v0, v48, 1.0
	v_fmac_f32_e32 v48, v49, v48
	v_div_scale_f32 v49, vcc, 1.0, v47, 1.0
	v_mul_f32_e32 v70, v49, v48
	v_fma_f32 v71, -v0, v70, v49
	v_fmac_f32_e32 v70, v71, v48
	v_fma_f32 v0, -v0, v70, v49
	v_div_fmas_f32 v0, v0, v48, v70
	v_div_fixup_f32 v0, v0, v47, 1.0
	v_div_scale_f32 v47, s[10:11], v46, v46, 1.0
	v_rcp_f32_e32 v48, v47
	s_nop 0
	v_fma_f32 v49, -v47, v48, 1.0
	v_fmac_f32_e32 v48, v49, v48
	v_div_scale_f32 v49, vcc, 1.0, v46, 1.0
	v_mul_f32_e32 v70, v49, v48
	v_fma_f32 v71, -v47, v70, v49
	v_fmac_f32_e32 v70, v71, v48
	v_fma_f32 v47, -v47, v70, v49
	v_div_fmas_f32 v47, v47, v48, v70
	v_div_fixup_f32 v46, v47, v46, 1.0
	v_cvt_pk_bf16_f32 v129, v46, v0
	v_add_f32_e32 v0, v66, v18
; DI float sigmoidf_(float x) { return 1.f / (1.f + __expf(-x)); }
; __global__ void __launch_bounds__(512, 2) mega(Params P) {
;     ...
;           const float* bgp = P.b_pg + L * DM;
;           EPI_LOOP_BEGIN EPI_SWAP_IDX
;             f32x4 bb = *reinterpret_cast<const f32x4*>(bgp + nb);
;             (void)m;
;             gatepk[mt][nt][2 * g] = pack2(sigmoidf_(acc[mt][nt][4 * g] + bb[0]), sigmoidf_(acc[mt][nt][4 * g + 1] + bb[1]));
;             gatepk[mt][nt][2 * g + 1] = pack2(sigmoidf_(acc[mt][nt][4 * g + 2] + bb[2]), sigmoidf_(acc[mt][nt][4 * g + 3] + bb[3]));
;           EPI_LOOP_END
	v_mul_f32_e32 v0, 0xbfb8aa3b, v0
	v_exp_f32_e32 v18, v0
	v_add_f32_e32 v0, v67, v19
	v_mul_f32_e32 v0, 0xbfb8aa3b, v0
	v_exp_f32_e32 v19, v0
	s_nop 0
	v_pk_add_f32 v[18:19], v[18:19], 1.0 op_sel_hi:[1,0]
	s_nop 0
	v_div_scale_f32 v0, s[10:11], v19, v19, 1.0
	v_rcp_f32_e32 v46, v0
	s_nop 0
	v_fma_f32 v47, -v0, v46, 1.0
	v_fmac_f32_e32 v46, v47, v46
	v_div_scale_f32 v47, vcc, 1.0, v19, 1.0
	v_mul_f32_e32 v48, v47, v46
	v_fma_f32 v49, -v0, v48, v47
	v_fmac_f32_e32 v48, v49, v46
	v_fma_f32 v0, -v0, v48, v47
	v_div_fmas_f32 v0, v0, v46, v48
	v_div_fixup_f32 v0, v0, v19, 1.0
	v_div_scale_f32 v19, s[10:11], v18, v18, 1.0
	v_rcp_f32_e32 v46, v19
	s_nop 0
	v_fma_f32 v47, -v19, v46, 1.0
	v_fmac_f32_e32 v46, v47, v46
	v_div_scale_f32 v47, vcc, 1.0, v18, 1.0
	v_mul_f32_e32 v48, v47, v46
	v_fma_f32 v49, -v19, v48, v47
	v_fmac_f32_e32 v48, v49, v46
	v_fma_f32 v19, -v19, v48, v47
	v_div_fmas_f32 v19, v19, v46, v48
	v_div_fixup_f32 v18, v19, v18, 1.0
	v_cvt_pk_bf16_f32 v130, v18, v0
	v_add_f32_e32 v0, v68, v20
	v_mul_f32_e32 v0, 0xbfb8aa3b, v0
	v_exp_f32_e32 v18, v0
	v_add_f32_e32 v0, v69, v21
	v_mul_f32_e32 v0, 0xbfb8aa3b, v0
	v_exp_f32_e32 v19, v0
	s_nop 0
	v_pk_add_f32 v[18:19], v[18:19], 1.0 op_sel_hi:[1,0]
	s_nop 0
	v_div_scale_f32 v0, s[10:11], v19, v19, 1.0
	v_rcp_f32_e32 v20, v0
	s_nop 0
	v_fma_f32 v21, -v0, v20, 1.0
	v_fmac_f32_e32 v20, v21, v20
	v_div_scale_f32 v21, vcc, 1.0, v19, 1.0
	v_mul_f32_e32 v46, v21, v20
	v_fma_f32 v47, -v0, v46, v21
	v_fmac_f32_e32 v46, v47, v20
	v_fma_f32 v0, -v0, v46, v21
	v_div_fmas_f32 v0, v0, v20, v46
	v_div_fixup_f32 v0, v0, v19, 1.0
	v_div_scale_f32 v19, s[10:11], v18, v18, 1.0
	v_rcp_f32_e32 v20, v19
	s_nop 0
	v_fma_f32 v21, -v19, v20, 1.0
	v_fmac_f32_e32 v20, v21, v20
	v_div_scale_f32 v21, vcc, 1.0, v18, 1.0
	v_mul_f32_e32 v46, v21, v20
	v_fma_f32 v47, -v19, v46, v21
	v_fmac_f32_e32 v46, v47, v20
	v_fma_f32 v19, -v19, v46, v21
	v_div_fmas_f32 v19, v19, v20, v46
	v_div_fixup_f32 v18, v19, v18, 1.0
	v_cvt_pk_bf16_f32 v131, v18, v0
	v_add_f32_e32 v0, v50, v22
	v_mul_f32_e32 v0, 0xbfb8aa3b, v0
	v_exp_f32_e32 v18, v0
	v_add_f32_e32 v0, v51, v23
	v_mul_f32_e32 v0, 0xbfb8aa3b, v0
	v_exp_f32_e32 v19, v0
	s_nop 0
	v_pk_add_f32 v[18:19], v[18:19], 1.0 op_sel_hi:[1,0]
	s_nop 0
	v_div_scale_f32 v0, s[10:11], v19, v19, 1.0
	v_rcp_f32_e32 v20, v0
	s_nop 0
	v_fma_f32 v21, -v0, v20, 1.0
	v_fmac_f32_e32 v20, v21, v20
	v_div_scale_f32 v21, vcc, 1.0, v19, 1.0
	v_mul_f32_e32 v22, v21, v20
	v_fma_f32 v23, -v0, v22, v21
	v_fmac_f32_e32 v22, v23, v20
	v_fma_f32 v0, -v0, v22, v21
	v_div_fmas_f32 v0, v0, v20, v22
	v_div_fixup_f32 v0, v0, v19, 1.0
	v_div_scale_f32 v19, s[10:11], v18, v18, 1.0
	v_rcp_f32_e32 v20, v19
	s_nop 0
	v_fma_f32 v21, -v19, v20, 1.0
	v_fmac_f32_e32 v20, v21, v20
	v_div_scale_f32 v21, vcc, 1.0, v18, 1.0
	v_mul_f32_e32 v22, v21, v20
	v_fma_f32 v23, -v19, v22, v21
	v_fmac_f32_e32 v22, v23, v20
	v_fma_f32 v19, -v19, v22, v21
	v_div_fmas_f32 v19, v19, v20, v22
	v_div_fixup_f32 v18, v19, v18, 1.0
	v_cvt_pk_bf16_f32 v132, v18, v0
	v_add_f32_e32 v0, v52, v24
	v_mul_f32_e32 v0, 0xbfb8aa3b, v0
	v_exp_f32_e32 v18, v0
	v_add_f32_e32 v0, v53, v25
	v_mul_f32_e32 v0, 0xbfb8aa3b, v0
	v_exp_f32_e32 v19, v0
	s_nop 0
	v_pk_add_f32 v[18:19], v[18:19], 1.0 op_sel_hi:[1,0]
	s_nop 0
	v_div_scale_f32 v0, s[10:11], v19, v19, 1.0
	v_rcp_f32_e32 v20, v0
	s_nop 0
	v_fma_f32 v21, -v0, v20, 1.0
	v_fmac_f32_e32 v20, v21, v20
	v_div_scale_f32 v21, vcc, 1.0, v19, 1.0
	v_mul_f32_e32 v22, v21, v20
	v_fma_f32 v23, -v0, v22, v21
	v_fmac_f32_e32 v22, v23, v20
	v_fma_f32 v0, -v0, v22, v21
	v_div_fmas_f32 v0, v0, v20, v22
	v_div_fixup_f32 v0, v0, v19, 1.0
	v_div_scale_f32 v19, s[10:11], v18, v18, 1.0
	v_rcp_f32_e32 v20, v19
	s_nop 0
	v_fma_f32 v21, -v19, v20, 1.0
	v_fmac_f32_e32 v20, v21, v20
	v_div_scale_f32 v21, vcc, 1.0, v18, 1.0
	v_mul_f32_e32 v22, v21, v20
	v_fma_f32 v23, -v19, v22, v21
	v_fmac_f32_e32 v22, v23, v20
	v_fma_f32 v19, -v19, v22, v21
	v_div_fmas_f32 v19, v19, v20, v22
	v_div_fixup_f32 v18, v19, v18, 1.0
	v_cvt_pk_bf16_f32 v133, v18, v0
	v_add_f32_e32 v0, v54, v26
	v_mul_f32_e32 v0, 0xbfb8aa3b, v0
	v_exp_f32_e32 v18, v0
	v_add_f32_e32 v0, v55, v27
	v_mul_f32_e32 v0, 0xbfb8aa3b, v0
	v_exp_f32_e32 v19, v0
	s_nop 0
	v_pk_add_f32 v[18:19], v[18:19], 1.0 op_sel_hi:[1,0]
	s_nop 0
	v_div_scale_f32 v0, s[10:11], v19, v19, 1.0
	v_rcp_f32_e32 v20, v0
	s_nop 0
	v_fma_f32 v21, -v0, v20, 1.0
	v_fmac_f32_e32 v20, v21, v20
	v_div_scale_f32 v21, vcc, 1.0, v19, 1.0
	v_mul_f32_e32 v22, v21, v20
	v_fma_f32 v23, -v0, v22, v21
	v_fmac_f32_e32 v22, v23, v20
	v_fma_f32 v0, -v0, v22, v21
	v_div_fmas_f32 v0, v0, v20, v22
	v_div_fixup_f32 v0, v0, v19, 1.0
	v_div_scale_f32 v19, s[10:11], v18, v18, 1.0
	v_rcp_f32_e32 v20, v19
	s_nop 0
	v_fma_f32 v21, -v19, v20, 1.0
	v_fmac_f32_e32 v20, v21, v20
	v_div_scale_f32 v21, vcc, 1.0, v18, 1.0
	v_mul_f32_e32 v22, v21, v20
	v_fma_f32 v23, -v19, v22, v21
	v_fmac_f32_e32 v22, v23, v20
	v_fma_f32 v19, -v19, v22, v21
	v_div_fmas_f32 v19, v19, v20, v22
	v_div_fixup_f32 v18, v19, v18, 1.0
	v_cvt_pk_bf16_f32 v134, v18, v0
	v_add_f32_e32 v0, v56, v28
	v_mul_f32_e32 v0, 0xbfb8aa3b, v0
	v_exp_f32_e32 v18, v0
	v_add_f32_e32 v0, v57, v29
	v_mul_f32_e32 v0, 0xbfb8aa3b, v0
	v_exp_f32_e32 v19, v0
	s_nop 0
	v_pk_add_f32 v[18:19], v[18:19], 1.0 op_sel_hi:[1,0]
	s_nop 0
	v_div_scale_f32 v0, s[10:11], v19, v19, 1.0
	v_rcp_f32_e32 v20, v0
	s_nop 0
	v_fma_f32 v21, -v0, v20, 1.0
	v_fmac_f32_e32 v20, v21, v20
	v_div_scale_f32 v21, vcc, 1.0, v19, 1.0
	v_mul_f32_e32 v22, v21, v20
	v_fma_f32 v23, -v0, v22, v21
	v_fmac_f32_e32 v22, v23, v20
	v_fma_f32 v0, -v0, v22, v21
	v_div_fmas_f32 v0, v0, v20, v22
	v_div_fixup_f32 v0, v0, v19, 1.0
; DI float sigmoidf_(float x) { return 1.f / (1.f + __expf(-x)); }
; __global__ void __launch_bounds__(512, 2) mega(Params P) {
;     ...
;           const float* bgp = P.b_pg + L * DM;
;           EPI_LOOP_BEGIN EPI_SWAP_IDX
;             f32x4 bb = *reinterpret_cast<const f32x4*>(bgp + nb);
;             (void)m;
;             gatepk[mt][nt][2 * g] = pack2(sigmoidf_(acc[mt][nt][4 * g] + bb[0]), sigmoidf_(acc[mt][nt][4 * g + 1] + bb[1]));
;             gatepk[mt][nt][2 * g + 1] = pack2(sigmoidf_(acc[mt][nt][4 * g + 2] + bb[2]), sigmoidf_(acc[mt][nt][4 * g + 3] + bb[3]));
;           EPI_LOOP_END
	v_div_scale_f32 v19, s[10:11], v18, v18, 1.0
	v_rcp_f32_e32 v20, v19
	s_nop 0
	v_fma_f32 v21, -v19, v20, 1.0
	v_fmac_f32_e32 v20, v21, v20
	v_div_scale_f32 v21, vcc, 1.0, v18, 1.0
	v_mul_f32_e32 v22, v21, v20
	v_fma_f32 v23, -v19, v22, v21
	v_fmac_f32_e32 v22, v23, v20
	v_fma_f32 v19, -v19, v22, v21
	v_div_fmas_f32 v19, v19, v20, v22
	v_div_fixup_f32 v18, v19, v18, 1.0
	v_cvt_pk_bf16_f32 v135, v18, v0
	v_add_f32_e32 v0, v58, v30
	v_mul_f32_e32 v0, 0xbfb8aa3b, v0
	v_exp_f32_e32 v18, v0
	v_add_f32_e32 v0, v59, v31
	v_mul_f32_e32 v0, 0xbfb8aa3b, v0
	v_exp_f32_e32 v19, v0
	s_nop 0
	v_pk_add_f32 v[18:19], v[18:19], 1.0 op_sel_hi:[1,0]
	s_nop 0
	v_div_scale_f32 v0, s[10:11], v19, v19, 1.0
	v_rcp_f32_e32 v20, v0
	s_nop 0
	v_fma_f32 v21, -v0, v20, 1.0
	v_fmac_f32_e32 v20, v21, v20
	v_div_scale_f32 v21, vcc, 1.0, v19, 1.0
	v_mul_f32_e32 v22, v21, v20
	v_fma_f32 v23, -v0, v22, v21
	v_fmac_f32_e32 v22, v23, v20
	v_fma_f32 v0, -v0, v22, v21
	v_div_fmas_f32 v0, v0, v20, v22
	v_div_fixup_f32 v0, v0, v19, 1.0
	v_div_scale_f32 v19, s[10:11], v18, v18, 1.0
	v_rcp_f32_e32 v20, v19
	s_nop 0
	v_fma_f32 v21, -v19, v20, 1.0
	v_fmac_f32_e32 v20, v21, v20
	v_div_scale_f32 v21, vcc, 1.0, v18, 1.0
	v_mul_f32_e32 v22, v21, v20
	v_fma_f32 v23, -v19, v22, v21
	v_fmac_f32_e32 v22, v23, v20
	v_fma_f32 v19, -v19, v22, v21
	v_div_fmas_f32 v19, v19, v20, v22
	v_div_fixup_f32 v18, v19, v18, 1.0
	v_cvt_pk_bf16_f32 v136, v18, v0
	v_add_f32_e32 v0, v60, v32
	v_mul_f32_e32 v0, 0xbfb8aa3b, v0
	v_exp_f32_e32 v18, v0
	v_add_f32_e32 v0, v61, v33
	v_mul_f32_e32 v0, 0xbfb8aa3b, v0
	v_exp_f32_e32 v19, v0
	s_nop 0
	v_pk_add_f32 v[18:19], v[18:19], 1.0 op_sel_hi:[1,0]
	s_nop 0
	v_div_scale_f32 v0, s[10:11], v19, v19, 1.0
	v_rcp_f32_e32 v20, v0
	s_nop 0
	v_fma_f32 v21, -v0, v20, 1.0
	v_fmac_f32_e32 v20, v21, v20
	v_div_scale_f32 v21, vcc, 1.0, v19, 1.0
	v_mul_f32_e32 v22, v21, v20
	v_fma_f32 v23, -v0, v22, v21
	v_fmac_f32_e32 v22, v23, v20
	v_fma_f32 v0, -v0, v22, v21
	v_div_fmas_f32 v0, v0, v20, v22
	v_div_fixup_f32 v0, v0, v19, 1.0
	v_div_scale_f32 v19, s[10:11], v18, v18, 1.0
	v_rcp_f32_e32 v20, v19
	s_nop 0
	v_fma_f32 v21, -v19, v20, 1.0
	v_fmac_f32_e32 v20, v21, v20
	v_div_scale_f32 v21, vcc, 1.0, v18, 1.0
	v_mul_f32_e32 v22, v21, v20
	v_fma_f32 v23, -v19, v22, v21
	v_fmac_f32_e32 v22, v23, v20
	v_fma_f32 v19, -v19, v22, v21
	v_div_fmas_f32 v19, v19, v20, v22
	v_div_fixup_f32 v18, v19, v18, 1.0
	v_cvt_pk_bf16_f32 v137, v18, v0
	v_add_f32_e32 v0, v62, v2
	v_mul_f32_e32 v0, 0xbfb8aa3b, v0
	v_exp_f32_e32 v2, v0
	v_add_f32_e32 v0, v63, v3
	v_mul_f32_e32 v0, 0xbfb8aa3b, v0
	v_exp_f32_e32 v3, v0
	s_nop 0
	v_pk_add_f32 v[2:3], v[2:3], 1.0 op_sel_hi:[1,0]
	s_nop 0
	v_div_scale_f32 v0, s[10:11], v3, v3, 1.0
	v_rcp_f32_e32 v18, v0
	s_nop 0
	v_fma_f32 v19, -v0, v18, 1.0
	v_fmac_f32_e32 v18, v19, v18
	v_div_scale_f32 v19, vcc, 1.0, v3, 1.0
	v_mul_f32_e32 v20, v19, v18
	v_fma_f32 v21, -v0, v20, v19
	v_fmac_f32_e32 v20, v21, v18
	v_fma_f32 v0, -v0, v20, v19
	v_div_fmas_f32 v0, v0, v18, v20
	v_div_fixup_f32 v0, v0, v3, 1.0
	v_div_scale_f32 v3, s[10:11], v2, v2, 1.0
	v_rcp_f32_e32 v18, v3
	s_nop 0
	v_fma_f32 v19, -v3, v18, 1.0
	v_fmac_f32_e32 v18, v19, v18
	v_div_scale_f32 v19, vcc, 1.0, v2, 1.0
	v_mul_f32_e32 v20, v19, v18
	v_fma_f32 v21, -v3, v20, v19
	v_fmac_f32_e32 v20, v21, v18
	v_fma_f32 v3, -v3, v20, v19
	v_div_fmas_f32 v3, v3, v18, v20
	v_div_fixup_f32 v2, v3, v2, 1.0
	v_cvt_pk_bf16_f32 v140, v2, v0
	v_add_f32_e32 v0, v64, v4
	v_mul_f32_e32 v0, 0xbfb8aa3b, v0
	v_exp_f32_e32 v2, v0
	v_add_f32_e32 v0, v65, v5
	v_mul_f32_e32 v0, 0xbfb8aa3b, v0
	v_exp_f32_e32 v3, v0
	s_nop 0
	v_pk_add_f32 v[2:3], v[2:3], 1.0 op_sel_hi:[1,0]
	s_nop 0
	v_div_scale_f32 v0, s[10:11], v3, v3, 1.0
	v_rcp_f32_e32 v4, v0
	s_nop 0
	v_fma_f32 v5, -v0, v4, 1.0
	v_fmac_f32_e32 v4, v5, v4
	v_div_scale_f32 v5, vcc, 1.0, v3, 1.0
	v_mul_f32_e32 v18, v5, v4
	v_fma_f32 v19, -v0, v18, v5
	v_fmac_f32_e32 v18, v19, v4
	v_fma_f32 v0, -v0, v18, v5
	v_div_fmas_f32 v0, v0, v4, v18
	v_div_fixup_f32 v0, v0, v3, 1.0
	v_div_scale_f32 v3, s[10:11], v2, v2, 1.0
	v_rcp_f32_e32 v4, v3
	s_nop 0
	v_fma_f32 v5, -v3, v4, 1.0
	v_fmac_f32_e32 v4, v5, v4
	v_div_scale_f32 v5, vcc, 1.0, v2, 1.0
	v_mul_f32_e32 v18, v5, v4
	v_fma_f32 v19, -v3, v18, v5
	v_fmac_f32_e32 v18, v19, v4
	v_fma_f32 v3, -v3, v18, v5
	v_div_fmas_f32 v3, v3, v4, v18
	v_div_fixup_f32 v2, v3, v2, 1.0
	v_cvt_pk_bf16_f32 v141, v2, v0
	v_add_f32_e32 v0, v34, v6
	v_mul_f32_e32 v0, 0xbfb8aa3b, v0
	v_exp_f32_e32 v2, v0
	v_add_f32_e32 v0, v35, v7
	v_mul_f32_e32 v0, 0xbfb8aa3b, v0
	v_exp_f32_e32 v3, v0
	v_mov_b32_e32 v34, v159
	v_pk_add_f32 v[2:3], v[2:3], 1.0 op_sel_hi:[1,0]
	s_nop 0
	v_div_scale_f32 v0, s[10:11], v3, v3, 1.0
	v_rcp_f32_e32 v4, v0
	v_bfe_u32 v35, v34, 3, 5
	v_fma_f32 v5, -v0, v4, 1.0
	v_fmac_f32_e32 v4, v5, v4
	v_div_scale_f32 v5, vcc, 1.0, v3, 1.0
	v_mul_f32_e32 v6, v5, v4
	v_fma_f32 v7, -v0, v6, v5
	v_fmac_f32_e32 v6, v7, v4
	v_fma_f32 v0, -v0, v6, v5
	v_div_fmas_f32 v0, v0, v4, v6
	v_div_fixup_f32 v0, v0, v3, 1.0
	v_div_scale_f32 v3, s[10:11], v2, v2, 1.0
	v_rcp_f32_e32 v4, v3
	s_nop 0
	v_fma_f32 v5, -v3, v4, 1.0
	v_fmac_f32_e32 v4, v5, v4
	v_div_scale_f32 v5, vcc, 1.0, v2, 1.0
	v_mul_f32_e32 v6, v5, v4
	v_fma_f32 v7, -v3, v6, v5
	v_fmac_f32_e32 v6, v7, v4
	v_fma_f32 v3, -v3, v6, v5
	v_div_fmas_f32 v3, v3, v4, v6
	v_div_fixup_f32 v2, v3, v2, 1.0
	v_cvt_pk_bf16_f32 v142, v2, v0
	v_add_f32_e32 v0, v36, v8
	v_mul_f32_e32 v0, 0xbfb8aa3b, v0
	v_exp_f32_e32 v2, v0
	v_add_f32_e32 v0, v37, v9
	v_mul_f32_e32 v0, 0xbfb8aa3b, v0
	v_exp_f32_e32 v3, v0
	v_and_b32_e32 v36, 31, v34
	v_pk_add_f32 v[2:3], v[2:3], 1.0 op_sel_hi:[1,0]
	s_nop 0
	v_div_scale_f32 v0, s[10:11], v3, v3, 1.0
; DI float sigmoidf_(float x) { return 1.f / (1.f + __expf(-x)); }
; template <int AMODE, bool SWAP>
; DI void gemm_core(const u16* __restrict__ A, int lda, const u16* __restrict__ Bt, int ldb, int K, int m0, int n0, int acol,
;                   f32x16 (&acc)[2][2], u16* sA, u16* sB) {
;     ...
;   auto gload = [&](int kt, u32x4 (&xa)[4], u32x4 (&xb)[4]) {
; #pragma unroll
;     for (int i = 0; i < 4; ++i) {
;       const int id = tid + 256 * i, row = id >> 3, ch = id & 7;
;       const u16* ap;
;       if (AMODE == 0) ap = A + (size_t)(m0 + row) * lda + kt * 64 + ch * 8;
;       else { int tok = 16 * (m0 + row) + kt; tok = tok < SEQ - 1 ? tok : SEQ - 1; ap = A + (size_t)tok * lda + acol + ch * 8; }
;       xa[i] = *reinterpret_cast<const u32x4*>(ap);
;       xb[i] = *reinterpret_cast<const u32x4*>(Bt + (size_t)(n0 + row) * ldb + kt * 64 + ch * 8);
;     }
;   };
;   auto stage = [&](const u32x4 (&xa)[4], const u32x4 (&xb)[4]) {
; #pragma unroll
;     for (int i = 0; i < 4; ++i) {
;       const int id = tid + 256 * i, row = id >> 3, ch = id & 7;
;       *reinterpret_cast<u32x4*>(sA + row * LDT + ch * 8) = xa[i];
;       *reinterpret_cast<u32x4*>(sB + row * LDT + ch * 8) = xb[i];
;     }
; __global__ void __launch_bounds__(512, 2) mega(Params P) {
;     ...
;             gatepk[mt][nt][2 * g] = pack2(sigmoidf_(acc[mt][nt][4 * g] + bb[0]), sigmoidf_(acc[mt][nt][4 * g + 1] + bb[1]));
;             gatepk[mt][nt][2 * g + 1] = pack2(sigmoidf_(acc[mt][nt][4 * g + 2] + bb[2]), sigmoidf_(acc[mt][nt][4 * g + 3] + bb[3]));
;           EPI_LOOP_END
;         }
;         zero_acc(acc);
;         gemm_core<0, true>(PB, 256, WPP, 256, 256, m0, n0, 0, acc, sA, sB);
	v_rcp_f32_e32 v4, v0
	s_nop 0
	v_fma_f32 v5, -v0, v4, 1.0
	v_fmac_f32_e32 v4, v5, v4
	v_div_scale_f32 v5, vcc, 1.0, v3, 1.0
	v_mul_f32_e32 v6, v5, v4
	v_fma_f32 v7, -v0, v6, v5
	v_fmac_f32_e32 v6, v7, v4
	v_fma_f32 v0, -v0, v6, v5
	v_div_fmas_f32 v0, v0, v4, v6
	v_div_fixup_f32 v0, v0, v3, 1.0
	v_div_scale_f32 v3, s[10:11], v2, v2, 1.0
	v_rcp_f32_e32 v4, v3
	s_nop 0
	v_fma_f32 v5, -v3, v4, 1.0
	v_fmac_f32_e32 v4, v5, v4
	v_div_scale_f32 v5, vcc, 1.0, v2, 1.0
	v_mul_f32_e32 v6, v5, v4
	v_fma_f32 v7, -v3, v6, v5
	v_fmac_f32_e32 v6, v7, v4
	v_fma_f32 v3, -v3, v6, v5
	v_div_fmas_f32 v3, v3, v4, v6
	v_div_fixup_f32 v2, v3, v2, 1.0
	v_cvt_pk_bf16_f32 v143, v2, v0
	v_add_f32_e32 v0, v38, v10
	v_mul_f32_e32 v0, 0xbfb8aa3b, v0
	v_exp_f32_e32 v2, v0
	v_add_f32_e32 v0, v39, v11
	v_mul_f32_e32 v0, 0xbfb8aa3b, v0
	v_exp_f32_e32 v3, v0
	s_nop 0
	v_pk_add_f32 v[2:3], v[2:3], 1.0 op_sel_hi:[1,0]
	s_nop 0
	v_div_scale_f32 v0, s[10:11], v3, v3, 1.0
	v_rcp_f32_e32 v4, v0
	s_nop 0
	v_fma_f32 v5, -v0, v4, 1.0
	v_fmac_f32_e32 v4, v5, v4
	v_div_scale_f32 v5, vcc, 1.0, v3, 1.0
	v_mul_f32_e32 v6, v5, v4
	v_fma_f32 v7, -v0, v6, v5
	v_fmac_f32_e32 v6, v7, v4
	v_fma_f32 v0, -v0, v6, v5
	v_div_fmas_f32 v0, v0, v4, v6
	v_div_fixup_f32 v0, v0, v3, 1.0
	v_div_scale_f32 v3, s[10:11], v2, v2, 1.0
	v_rcp_f32_e32 v4, v3
	s_nop 0
	v_fma_f32 v5, -v3, v4, 1.0
	v_fmac_f32_e32 v4, v5, v4
	v_div_scale_f32 v5, vcc, 1.0, v2, 1.0
	v_mul_f32_e32 v6, v5, v4
	v_fma_f32 v7, -v3, v6, v5
	v_fmac_f32_e32 v6, v7, v4
	v_fma_f32 v3, -v3, v6, v5
	v_div_fmas_f32 v3, v3, v4, v6
	v_div_fixup_f32 v2, v3, v2, 1.0
	v_cvt_pk_bf16_f32 v144, v2, v0
	v_add_f32_e32 v0, v40, v12
	v_mul_f32_e32 v0, 0xbfb8aa3b, v0
	v_exp_f32_e32 v2, v0
	v_add_f32_e32 v0, v41, v13
	v_mul_f32_e32 v0, 0xbfb8aa3b, v0
	v_exp_f32_e32 v3, v0
	s_nop 0
	v_pk_add_f32 v[2:3], v[2:3], 1.0 op_sel_hi:[1,0]
	s_nop 0
	v_div_scale_f32 v0, s[10:11], v3, v3, 1.0
	v_rcp_f32_e32 v4, v0
	s_nop 0
	v_fma_f32 v5, -v0, v4, 1.0
	v_fmac_f32_e32 v4, v5, v4
	v_div_scale_f32 v5, vcc, 1.0, v3, 1.0
	v_mul_f32_e32 v6, v5, v4
	v_fma_f32 v7, -v0, v6, v5
	v_fmac_f32_e32 v6, v7, v4
	v_fma_f32 v0, -v0, v6, v5
	v_div_fmas_f32 v0, v0, v4, v6
	v_div_fixup_f32 v0, v0, v3, 1.0
	v_div_scale_f32 v3, s[10:11], v2, v2, 1.0
	v_rcp_f32_e32 v4, v3
	s_nop 0
	v_fma_f32 v5, -v3, v4, 1.0
	v_fmac_f32_e32 v4, v5, v4
	v_div_scale_f32 v5, vcc, 1.0, v2, 1.0
	v_mul_f32_e32 v6, v5, v4
	v_fma_f32 v7, -v3, v6, v5
	v_fmac_f32_e32 v6, v7, v4
	v_fma_f32 v3, -v3, v6, v5
	v_div_fmas_f32 v3, v3, v4, v6
	v_div_fixup_f32 v2, v3, v2, 1.0
	v_cvt_pk_bf16_f32 v145, v2, v0
	v_add_f32_e32 v0, v42, v14
	v_mul_f32_e32 v0, 0xbfb8aa3b, v0
	v_exp_f32_e32 v2, v0
	v_add_f32_e32 v0, v43, v15
	v_mul_f32_e32 v0, 0xbfb8aa3b, v0
	v_exp_f32_e32 v3, v0
	s_nop 0
	v_pk_add_f32 v[2:3], v[2:3], 1.0 op_sel_hi:[1,0]
	s_nop 0
	v_div_scale_f32 v0, s[10:11], v3, v3, 1.0
	v_rcp_f32_e32 v4, v0
	s_nop 0
	v_fma_f32 v5, -v0, v4, 1.0
	v_fmac_f32_e32 v4, v5, v4
	v_div_scale_f32 v5, vcc, 1.0, v3, 1.0
	v_mul_f32_e32 v6, v5, v4
	v_fma_f32 v7, -v0, v6, v5
	v_fmac_f32_e32 v6, v7, v4
	v_fma_f32 v0, -v0, v6, v5
	v_div_fmas_f32 v0, v0, v4, v6
	v_div_fixup_f32 v0, v0, v3, 1.0
	v_div_scale_f32 v3, s[10:11], v2, v2, 1.0
	v_rcp_f32_e32 v4, v3
	s_nop 0
	v_fma_f32 v5, -v3, v4, 1.0
	v_fmac_f32_e32 v4, v5, v4
	v_div_scale_f32 v5, vcc, 1.0, v2, 1.0
	v_mul_f32_e32 v6, v5, v4
	v_fma_f32 v7, -v3, v6, v5
	v_fmac_f32_e32 v6, v7, v4
	v_fma_f32 v3, -v3, v6, v5
	v_div_fmas_f32 v3, v3, v4, v6
	v_div_fixup_f32 v2, v3, v2, 1.0
	v_cvt_pk_bf16_f32 v138, v2, v0
	v_add_f32_e32 v0, v44, v16
	v_mul_f32_e32 v0, 0xbfb8aa3b, v0
	v_exp_f32_e32 v2, v0
	v_add_f32_e32 v0, v45, v17
	v_mul_f32_e32 v0, 0xbfb8aa3b, v0
	v_exp_f32_e32 v3, v0
	s_nop 0
	v_pk_add_f32 v[2:3], v[2:3], 1.0 op_sel_hi:[1,0]
	s_nop 0
	v_div_scale_f32 v0, s[10:11], v3, v3, 1.0
	v_rcp_f32_e32 v4, v0
	s_nop 0
	v_fma_f32 v5, -v0, v4, 1.0
	v_fmac_f32_e32 v4, v5, v4
	v_div_scale_f32 v5, vcc, 1.0, v3, 1.0
	v_mul_f32_e32 v6, v5, v4
	v_fma_f32 v7, -v0, v6, v5
	v_fmac_f32_e32 v6, v7, v4
	v_fma_f32 v0, -v0, v6, v5
	v_div_fmas_f32 v0, v0, v4, v6
	v_div_fixup_f32 v0, v0, v3, 1.0
	v_div_scale_f32 v3, s[10:11], v2, v2, 1.0
	v_rcp_f32_e32 v4, v3
	v_readlane_b32 s10, v252, 44
	v_readlane_b32 s11, v252, 45
	v_fma_f32 v5, -v3, v4, 1.0
	v_fmac_f32_e32 v4, v5, v4
	v_div_scale_f32 v5, vcc, 1.0, v2, 1.0
	v_mul_f32_e32 v6, v5, v4
	v_fma_f32 v7, -v3, v6, v5
	v_fmac_f32_e32 v6, v7, v4
	v_fma_f32 v3, -v3, v6, v5
	v_div_fmas_f32 v3, v3, v4, v6
	v_div_fixup_f32 v2, v3, v2, 1.0
	v_cvt_pk_bf16_f32 v139, v2, v0
	v_or_b32_e32 v0, 32, v35
	v_or_b32_e32 v6, s22, v0
	v_or_b32_e32 v8, s21, v0
	v_or_b32_e32 v0, 64, v35
	v_or_b32_e32 v4, s21, v35
	v_or_b32_e32 v10, s22, v0
	v_or_b32_e32 v12, s21, v0
	v_or_b32_e32 v0, 0x60, v35
	v_or_b32_e32 v2, s22, v35
	v_ashrrev_i32_e32 v5, 31, v4
	v_or_b32_e32 v14, s22, v0
	v_or_b32_e32 v16, s21, v0
	v_ashrrev_i32_e32 v3, 31, v2
	v_lshlrev_b64 v[4:5], 9, v[4:5]
	v_ashrrev_i32_e32 v7, 31, v6
	v_ashrrev_i32_e32 v9, 31, v8
	v_ashrrev_i32_e32 v11, 31, v10
	v_ashrrev_i32_e32 v13, 31, v12
	v_ashrrev_i32_e32 v15, 31, v14
	v_ashrrev_i32_e32 v17, 31, v16
	v_lshlrev_b32_e32 v0, 4, v34
	v_lshlrev_b64 v[2:3], 9, v[2:3]
	v_lshl_add_u64 v[4:5], s[10:11], 0, v[4:5]
	v_lshlrev_b64 v[6:7], 9, v[6:7]
	v_lshlrev_b64 v[8:9], 9, v[8:9]
	v_lshlrev_b64 v[10:11], 9, v[10:11]
	v_lshlrev_b64 v[12:13], 9, v[12:13]
	v_lshlrev_b64 v[14:15], 9, v[14:15]
	v_lshlrev_b64 v[16:17], 9, v[16:17]
	v_and_b32_e32 v0, 0x70, v0
	v_lshl_add_u64 v[2:3], s[12:13], 0, v[2:3]
	v_lshl_add_u64 v[6:7], s[12:13], 0, v[6:7]
	v_lshl_add_u64 v[8:9], s[10:11], 0, v[8:9]
	v_lshl_add_u64 v[10:11], s[12:13], 0, v[10:11]
	v_lshl_add_u64 v[12:13], s[10:11], 0, v[12:13]
	v_lshl_add_u64 v[14:15], s[12:13], 0, v[14:15]
	v_lshl_add_u64 v[16:17], s[10:11], 0, v[16:17]
	v_lshl_add_u64 v[100:101], v[4:5], 0, v[0:1]
	v_lshl_add_u64 v[98:99], v[2:3], 0, v[0:1]
	v_lshl_add_u64 v[102:103], v[6:7], 0, v[0:1]
	v_lshl_add_u64 v[104:105], v[8:9], 0, v[0:1]
	v_lshl_add_u64 v[106:107], v[10:11], 0, v[0:1]
	v_lshl_add_u64 v[108:109], v[12:13], 0, v[0:1]
	v_lshl_add_u64 v[110:111], v[14:15], 0, v[0:1]
	v_lshl_add_u64 v[112:113], v[16:17], 0, v[0:1]
	global_load_dwordx4 v[14:17], v[100:101], off
	global_load_dwordx4 v[10:13], v[104:105], off
	global_load_dwordx4 v[6:9], v[108:109], off
	global_load_dwordx4 v[2:5], v[112:113], off
	global_load_dwordx4 v[18:21], v[98:99], off
	global_load_dwordx4 v[22:25], v[102:103], off
	global_load_dwordx4 v[26:29], v[106:107], off
	global_load_dwordx4 v[30:33], v[110:111], off
	v_mul_u32_u24_e32 v35, 0x48, v35
	v_lshlrev_b32_e32 v35, 1, v35
	v_add3_u32 v147, s42, v0, v35
	s_waitcnt vmcnt(3)
	ds_write_b128 v147, v[18:21]
	ds_write_b128 v147, v[14:17] offset:18432
	s_waitcnt vmcnt(2)
	ds_write_b128 v147, v[22:25] offset:4608
	ds_write_b128 v147, v[10:13] offset:23040
	s_waitcnt vmcnt(1)
	ds_write_b128 v147, v[26:29] offset:9216
	ds_write_b128 v147, v[6:9] offset:27648
	s_waitcnt vmcnt(0)
	ds_write_b128 v147, v[30:33] offset:13824
	ds_write_b128 v147, v[2:5] offset:32256
	s_waitcnt lgkmcnt(0)
	s_barrier
; #define MFMA32(a, b, c) __builtin_amdgcn_mfma_f32_32x32x16_bf16((a), (b), (c), 0, 0, 0)
; template <int AMODE, bool SWAP>
; DI void gemm_core(const u16* __restrict__ A, int lda, const u16* __restrict__ Bt, int ldb, int K, int m0, int n0, int acol,
;                   f32x16 (&acc)[2][2], u16* sA, u16* sB) {
;     ...
;   auto ldfrag = [&](int ks, bf16x8 (&af)[2], bf16x8 (&bfr)[2]) {
; #pragma unroll
;     for (int t = 0; t < 2; ++t) {
;       af[t] = ld16(sA + (wm * 64 + t * 32 + r) * LDT + ks * 16 + h2 * 8);
;       bfr[t] = ld16(sB + (wn * 64 + t * 32 + r) * LDT + ks * 16 + h2 * 8);
;     }
;   };
;   auto mm = [&](const bf16x8 (&af)[2], const bf16x8 (&bfr)[2]) {
; #pragma unroll
;     for (int mt = 0; mt < 2; ++mt)
; #pragma unroll
;       for (int nt = 0; nt < 2; ++nt) {
;         if (SWAP) acc[mt][nt] = MFMA32(bfr[nt], af[mt], acc[mt][nt]);
;         else acc[mt][nt] = MFMA32(af[mt], bfr[nt], acc[mt][nt]);
;       }
;   };
;   auto compute = [&]() {
;     bf16x8 a0[2], b0[2], a1[2], b1[2];
;     ldfrag(0, a0, b0);
;     ldfrag(1, a1, b1);
;     __builtin_amdgcn_sched_barrier(0);
;     mm(a0, b0);
;     __builtin_amdgcn_sched_barrier(0);
;     ldfrag(2, a0, b0);
;     __builtin_amdgcn_sched_barrier(0);
;     mm(a1, b1);
;     __builtin_amdgcn_sched_barrier(0);
;     ldfrag(3, a1, b1);
;     __builtin_amdgcn_sched_barrier(0);
;     mm(a0, b0);
;     mm(a1, b1);
;   };
;   gload(0, ra[0], rb[0]);
;   for (int kt = 0; kt < nk; ++kt) {
;     stage(ra[0], rb[0]);
;     __syncthreads();
;     if (kt + 1 < nk) gload(kt + 1, ra[0], rb[0]);
;     __builtin_amdgcn_sched_barrier(0);
;     compute();
;     __syncthreads();
;   }
	global_load_dwordx4 v[82:85], v[98:99], off offset:128
	global_load_dwordx4 v[86:89], v[100:101], off offset:128
	global_load_dwordx4 v[90:93], v[102:103], off offset:128
	global_load_dwordx4 v[94:97], v[104:105], off offset:128
	global_load_dwordx4 v[66:69], v[106:107], off offset:128
	global_load_dwordx4 v[70:73], v[108:109], off offset:128
	global_load_dwordx4 v[74:77], v[110:111], off offset:128
	global_load_dwordx4 v[78:81], v[112:113], off offset:128
	v_lshrrev_b32_e32 v0, 1, v34
	v_and_or_b32 v35, v0, 64, v36
	v_and_b32_e32 v34, 0x5f, v34
	v_mul_u32_u24_e32 v35, 0x90, v35
	v_and_b32_e32 v36, 16, v0
	v_mul_u32_u24_e32 v34, 0x90, v34
	v_add3_u32 v0, s42, v35, v36
	v_add3_u32 v146, s42, v34, v36
	ds_read_b128 v[2:5], v0
	ds_read_b128 v[148:151], v0 offset:32
	ds_read_b128 v[6:9], v146 offset:18432
	ds_read_b128 v[152:155], v146 offset:18464
	ds_read_b128 v[10:13], v0 offset:4608
	ds_read_b128 v[160:163], v0 offset:4640
	ds_read_b128 v[14:17], v146 offset:23040
	ds_read_b128 v[170:173], v146 offset:23072
	s_waitcnt lgkmcnt(5)
	v_mfma_f32_32x32x16_bf16 v[50:65], v[6:9], v[2:5], 0
	s_waitcnt lgkmcnt(1)
	v_mfma_f32_32x32x16_bf16 v[34:49], v[14:17], v[2:5], 0
	v_mfma_f32_32x32x16_bf16 v[18:33], v[6:9], v[10:13], 0
	v_mfma_f32_32x32x16_bf16 v[2:17], v[14:17], v[10:13], 0
	ds_read_b128 v[174:177], v0 offset:64
	ds_read_b128 v[190:193], v0 offset:4672
	ds_read_b128 v[194:197], v146 offset:18496
	ds_read_b128 v[198:201], v146 offset:23104
	v_mfma_f32_32x32x16_bf16 v[50:65], v[152:155], v[148:151], v[50:65]
	s_waitcnt lgkmcnt(4)
	v_mfma_f32_32x32x16_bf16 v[34:49], v[170:173], v[148:151], v[34:49]
	v_mfma_f32_32x32x16_bf16 v[18:33], v[152:155], v[160:163], v[18:33]
	v_mfma_f32_32x32x16_bf16 v[2:17], v[170:173], v[160:163], v[2:17]
	ds_read_b128 v[148:151], v0 offset:96
	ds_read_b128 v[152:155], v0 offset:4704
	ds_read_b128 v[160:163], v146 offset:18528
	ds_read_b128 v[170:173], v146 offset:23136
	s_waitcnt lgkmcnt(0)
	s_barrier
	s_waitcnt vmcnt(7)
	ds_write_b128 v147, v[82:85]
	s_waitcnt vmcnt(6)
	ds_write_b128 v147, v[86:89] offset:18432
	s_waitcnt vmcnt(5)
	ds_write_b128 v147, v[90:93] offset:4608
	s_waitcnt vmcnt(4)
	ds_write_b128 v147, v[94:97] offset:23040
	s_waitcnt vmcnt(3)
	ds_write_b128 v147, v[66:69] offset:9216
	s_waitcnt vmcnt(2)
	ds_write_b128 v147, v[70:73] offset:27648
	s_waitcnt vmcnt(1)
	ds_write_b128 v147, v[74:77] offset:13824
	s_waitcnt vmcnt(0)
	ds_write_b128 v147, v[78:81] offset:32256
	s_waitcnt lgkmcnt(0)
	s_barrier
	global_load_dwordx4 v[66:69], v[98:99], off offset:256
	global_load_dwordx4 v[70:73], v[100:101], off offset:256
	global_load_dwordx4 v[74:77], v[102:103], off offset:256
	global_load_dwordx4 v[78:81], v[104:105], off offset:256
	global_load_dwordx4 v[82:85], v[106:107], off offset:256
	global_load_dwordx4 v[86:89], v[108:109], off offset:256
	global_load_dwordx4 v[90:93], v[110:111], off offset:256
	global_load_dwordx4 v[94:97], v[112:113], off offset:256
	v_mfma_f32_32x32x16_bf16 v[50:65], v[194:197], v[174:177], v[50:65]
	v_mfma_f32_32x32x16_bf16 v[34:49], v[198:201], v[174:177], v[34:49]
	v_mfma_f32_32x32x16_bf16 v[18:33], v[194:197], v[190:193], v[18:33]
	v_mfma_f32_32x32x16_bf16 v[2:17], v[198:201], v[190:193], v[2:17]
	v_mfma_f32_32x32x16_bf16 v[50:65], v[160:163], v[148:151], v[50:65]
	v_mfma_f32_32x32x16_bf16 v[34:49], v[170:173], v[148:151], v[34:49]
	v_mfma_f32_32x32x16_bf16 v[18:33], v[160:163], v[152:155], v[18:33]
	v_mfma_f32_32x32x16_bf16 v[2:17], v[170:173], v[152:155], v[2:17]
	ds_read_b128 v[148:151], v0
	ds_read_b128 v[152:155], v0 offset:32
	ds_read_b128 v[160:163], v146 offset:18432
	ds_read_b128 v[170:173], v146 offset:18464
	ds_read_b128 v[174:177], v0 offset:4608
	ds_read_b128 v[190:193], v0 offset:4640
	ds_read_b128 v[194:197], v146 offset:23040
	ds_read_b128 v[198:201], v146 offset:23072
	s_waitcnt lgkmcnt(5)
	v_mfma_f32_32x32x16_bf16 v[50:65], v[160:163], v[148:151], v[50:65]
	s_waitcnt lgkmcnt(1)
	v_mfma_f32_32x32x16_bf16 v[34:49], v[194:197], v[148:151], v[34:49]
	v_mfma_f32_32x32x16_bf16 v[18:33], v[160:163], v[174:177], v[18:33]
	v_mfma_f32_32x32x16_bf16 v[2:17], v[194:197], v[174:177], v[2:17]
	ds_read_b128 v[148:151], v0 offset:64
	ds_read_b128 v[160:163], v0 offset:4672
	ds_read_b128 v[174:177], v146 offset:18496
	ds_read_b128 v[194:197], v146 offset:23104
	v_mfma_f32_32x32x16_bf16 v[50:65], v[170:173], v[152:155], v[50:65]
	s_waitcnt lgkmcnt(4)
	v_mfma_f32_32x32x16_bf16 v[34:49], v[198:201], v[152:155], v[34:49]
	v_mfma_f32_32x32x16_bf16 v[18:33], v[170:173], v[190:193], v[18:33]
	v_mfma_f32_32x32x16_bf16 v[2:17], v[198:201], v[190:193], v[2:17]
	ds_read_b128 v[152:155], v0 offset:96
	ds_read_b128 v[170:173], v0 offset:4704
	ds_read_b128 v[190:193], v146 offset:18528
	ds_read_b128 v[198:201], v146 offset:23136
	s_waitcnt lgkmcnt(0)
	s_barrier
	s_waitcnt vmcnt(7)
	ds_write_b128 v147, v[66:69]
	s_waitcnt vmcnt(6)
	ds_write_b128 v147, v[70:73] offset:18432
	s_waitcnt vmcnt(5)
	ds_write_b128 v147, v[74:77] offset:4608
	s_waitcnt vmcnt(4)
	ds_write_b128 v147, v[78:81] offset:23040
	s_waitcnt vmcnt(3)
	ds_write_b128 v147, v[82:85] offset:9216
	s_waitcnt vmcnt(2)
	ds_write_b128 v147, v[86:89] offset:27648
	s_waitcnt vmcnt(1)
	ds_write_b128 v147, v[90:93] offset:13824
	s_waitcnt vmcnt(0)
	ds_write_b128 v147, v[94:97] offset:32256
	s_waitcnt lgkmcnt(0)
	s_barrier
; #define MFMA32(a, b, c) __builtin_amdgcn_mfma_f32_32x32x16_bf16((a), (b), (c), 0, 0, 0)
; template <int AMODE, bool SWAP>
; DI void gemm_core(const u16* __restrict__ A, int lda, const u16* __restrict__ Bt, int ldb, int K, int m0, int n0, int acol,
;                   f32x16 (&acc)[2][2], u16* sA, u16* sB) {
;     ...
;   auto ldfrag = [&](int ks, bf16x8 (&af)[2], bf16x8 (&bfr)[2]) {
; #pragma unroll
;     for (int t = 0; t < 2; ++t) {
;       af[t] = ld16(sA + (wm * 64 + t * 32 + r) * LDT + ks * 16 + h2 * 8);
;       bfr[t] = ld16(sB + (wn * 64 + t * 32 + r) * LDT + ks * 16 + h2 * 8);
;     }
;   };
;   auto mm = [&](const bf16x8 (&af)[2], const bf16x8 (&bfr)[2]) {
; #pragma unroll
;     for (int mt = 0; mt < 2; ++mt)
; #pragma unroll
;       for (int nt = 0; nt < 2; ++nt) {
;         if (SWAP) acc[mt][nt] = MFMA32(bfr[nt], af[mt], acc[mt][nt]);
;         else acc[mt][nt] = MFMA32(af[mt], bfr[nt], acc[mt][nt]);
;       }
;   };
;   auto compute = [&]() {
;     bf16x8 a0[2], b0[2], a1[2], b1[2];
;     ldfrag(0, a0, b0);
;     ldfrag(1, a1, b1);
;     __builtin_amdgcn_sched_barrier(0);
;     mm(a0, b0);
;     __builtin_amdgcn_sched_barrier(0);
;     ldfrag(2, a0, b0);
;     __builtin_amdgcn_sched_barrier(0);
;     mm(a1, b1);
;     __builtin_amdgcn_sched_barrier(0);
;     ldfrag(3, a1, b1);
;     __builtin_amdgcn_sched_barrier(0);
;     mm(a0, b0);
;     mm(a1, b1);
;   };
;   gload(0, ra[0], rb[0]);
;   for (int kt = 0; kt < nk; ++kt) {
;     stage(ra[0], rb[0]);
;     __syncthreads();
;     if (kt + 1 < nk) gload(kt + 1, ra[0], rb[0]);
;     __builtin_amdgcn_sched_barrier(0);
;     compute();
;     __syncthreads();
;   }
	global_load_dwordx4 v[66:69], v[98:99], off offset:384
	global_load_dwordx4 v[70:73], v[100:101], off offset:384
	global_load_dwordx4 v[74:77], v[102:103], off offset:384
	global_load_dwordx4 v[78:81], v[104:105], off offset:384
	global_load_dwordx4 v[82:85], v[106:107], off offset:384
	global_load_dwordx4 v[86:89], v[108:109], off offset:384
	global_load_dwordx4 v[90:93], v[110:111], off offset:384
	global_load_dwordx4 v[94:97], v[112:113], off offset:384
	v_mfma_f32_32x32x16_bf16 v[50:65], v[174:177], v[148:151], v[50:65]
	v_mfma_f32_32x32x16_bf16 v[34:49], v[194:197], v[148:151], v[34:49]
	v_mfma_f32_32x32x16_bf16 v[18:33], v[174:177], v[160:163], v[18:33]
	v_mfma_f32_32x32x16_bf16 v[2:17], v[194:197], v[160:163], v[2:17]
	v_mfma_f32_32x32x16_bf16 v[50:65], v[190:193], v[152:155], v[50:65]
	v_mfma_f32_32x32x16_bf16 v[34:49], v[198:201], v[152:155], v[34:49]
	v_mfma_f32_32x32x16_bf16 v[18:33], v[190:193], v[170:173], v[18:33]
	v_mfma_f32_32x32x16_bf16 v[2:17], v[198:201], v[170:173], v[2:17]
	ds_read_b128 v[98:101], v0
	ds_read_b128 v[102:105], v0 offset:32
	ds_read_b128 v[106:109], v146 offset:18432
	ds_read_b128 v[110:113], v146 offset:18464
	ds_read_b128 v[148:151], v0 offset:4608
	ds_read_b128 v[152:155], v0 offset:4640
	ds_read_b128 v[160:163], v146 offset:23040
	ds_read_b128 v[170:173], v146 offset:23072
	s_waitcnt lgkmcnt(5)
	v_mfma_f32_32x32x16_bf16 v[50:65], v[106:109], v[98:101], v[50:65]
	s_waitcnt lgkmcnt(1)
	v_mfma_f32_32x32x16_bf16 v[34:49], v[160:163], v[98:101], v[34:49]
	v_mfma_f32_32x32x16_bf16 v[18:33], v[106:109], v[148:151], v[18:33]
	v_mfma_f32_32x32x16_bf16 v[2:17], v[160:163], v[148:151], v[2:17]
	ds_read_b128 v[98:101], v0 offset:64
	ds_read_b128 v[106:109], v0 offset:4672
	ds_read_b128 v[148:151], v146 offset:18496
	ds_read_b128 v[160:163], v146 offset:23104
	v_mfma_f32_32x32x16_bf16 v[50:65], v[110:113], v[102:105], v[50:65]
	s_waitcnt lgkmcnt(4)
	v_mfma_f32_32x32x16_bf16 v[34:49], v[170:173], v[102:105], v[34:49]
	v_mfma_f32_32x32x16_bf16 v[18:33], v[110:113], v[152:155], v[18:33]
	v_mfma_f32_32x32x16_bf16 v[2:17], v[170:173], v[152:155], v[2:17]
	ds_read_b128 v[102:105], v0 offset:96
	ds_read_b128 v[110:113], v0 offset:4704
	ds_read_b128 v[152:155], v146 offset:18528
	ds_read_b128 v[170:173], v146 offset:23136
	s_waitcnt lgkmcnt(5)
	v_mfma_f32_32x32x16_bf16 v[50:65], v[148:151], v[98:101], v[50:65]
	s_waitcnt lgkmcnt(0)
	s_barrier
	s_waitcnt vmcnt(7)
	ds_write_b128 v147, v[66:69]
	s_waitcnt vmcnt(6)
	ds_write_b128 v147, v[70:73] offset:18432
	s_waitcnt vmcnt(5)
	ds_write_b128 v147, v[74:77] offset:4608
	s_waitcnt vmcnt(4)
	ds_write_b128 v147, v[78:81] offset:23040
	s_waitcnt vmcnt(3)
	ds_write_b128 v147, v[82:85] offset:9216
	s_waitcnt vmcnt(2)
	ds_write_b128 v147, v[86:89] offset:27648
	s_waitcnt vmcnt(1)
	ds_write_b128 v147, v[90:93] offset:13824
	s_waitcnt vmcnt(0)
	ds_write_b128 v147, v[94:97] offset:32256
	s_waitcnt lgkmcnt(0)
	s_barrier
	v_mfma_f32_32x32x16_bf16 v[34:49], v[160:163], v[98:101], v[34:49]
	v_mfma_f32_32x32x16_bf16 v[18:33], v[148:151], v[106:109], v[18:33]
	v_mfma_f32_32x32x16_bf16 v[2:17], v[160:163], v[106:109], v[2:17]
	v_mfma_f32_32x32x16_bf16 v[50:65], v[152:155], v[102:105], v[50:65]
	v_mfma_f32_32x32x16_bf16 v[34:49], v[170:173], v[102:105], v[34:49]
	v_mfma_f32_32x32x16_bf16 v[18:33], v[152:155], v[110:113], v[18:33]
	v_mfma_f32_32x32x16_bf16 v[2:17], v[170:173], v[110:113], v[2:17]
	ds_read_b128 v[66:69], v0
	ds_read_b128 v[70:73], v0 offset:32
	ds_read_b128 v[74:77], v146 offset:18432
	ds_read_b128 v[78:81], v146 offset:18464
	ds_read_b128 v[82:85], v0 offset:4608
	ds_read_b128 v[86:89], v0 offset:4640
	ds_read_b128 v[90:93], v146 offset:23040
	ds_read_b128 v[94:97], v146 offset:23072
	s_waitcnt lgkmcnt(5)
	v_mfma_f32_32x32x16_bf16 v[50:65], v[74:77], v[66:69], v[50:65]
	s_waitcnt lgkmcnt(1)
	v_mfma_f32_32x32x16_bf16 v[34:49], v[90:93], v[66:69], v[34:49]
	v_mfma_f32_32x32x16_bf16 v[18:33], v[74:77], v[82:85], v[18:33]
	v_mfma_f32_32x32x16_bf16 v[2:17], v[90:93], v[82:85], v[2:17]
	ds_read_b128 v[66:69], v0 offset:64
	ds_read_b128 v[74:77], v0 offset:4672
	ds_read_b128 v[82:85], v146 offset:18496
	ds_read_b128 v[90:93], v146 offset:23104
	v_mfma_f32_32x32x16_bf16 v[50:65], v[78:81], v[70:73], v[50:65]
	s_waitcnt lgkmcnt(4)
	v_mfma_f32_32x32x16_bf16 v[34:49], v[94:97], v[70:73], v[34:49]
	v_mfma_f32_32x32x16_bf16 v[18:33], v[78:81], v[86:89], v[18:33]
	v_mfma_f32_32x32x16_bf16 v[2:17], v[94:97], v[86:89], v[2:17]
	ds_read_b128 v[70:73], v0 offset:96
	ds_read_b128 v[78:81], v0 offset:4704
	ds_read_b128 v[86:89], v146 offset:18528
	ds_read_b128 v[94:97], v146 offset:23136
	s_waitcnt lgkmcnt(5)
	v_mfma_f32_32x32x16_bf16 v[50:65], v[82:85], v[66:69], v[50:65]
	v_mov_b32_e32 v0, v159
	s_waitcnt lgkmcnt(0)
	s_barrier
; DI float bf2f(u16 v) { return __uint_as_float((u32)v << 16); }
; __global__ void __launch_bounds__(512, 2) mega(Params P) {
;     ...
;         EPI_LOOP_BEGIN EPI_SWAP_IDX
;           f32x4* hp = reinterpret_cast<f32x4*>(H + (size_t)m * DM + nb);
;           f32x4 hv = *hp;
;           const u32 g01 = gatepk[mt][nt][2 * g], g23 = gatepk[mt][nt][2 * g + 1];
;           hv[0] += acc[mt][nt][4 * g] * bf2f((u16)(g01 & 0xffffu));
;           hv[1] += acc[mt][nt][4 * g + 1] * bf2f((u16)(g01 >> 16));
;           hv[2] += acc[mt][nt][4 * g + 2] * bf2f((u16)(g23 & 0xffffu));
;           hv[3] += acc[mt][nt][4 * g + 3] * bf2f((u16)(g23 >> 16));
;           *hp = hv;
;         EPI_LOOP_END
	v_readlane_b32 s48, v255, 4
	v_readlane_b32 s60, v255, 16
	v_mfma_f32_32x32x16_bf16 v[34:49], v[90:93], v[66:69], v[34:49]
	v_mov_b32_e32 v66, v159
	v_and_b32_e32 v67, 31, v0
	v_and_b32_e32 v68, 64, v66
	v_lshrrev_b32_e32 v66, 1, v66
	v_and_b32_e32 v66, 64, v66
	v_lshrrev_b32_e32 v0, 3, v0
	v_or3_b32 v66, v66, v67, s22
	v_and_b32_e32 v0, 4, v0
	v_or3_b32 v68, v68, v0, s21
	v_ashrrev_i32_e32 v67, 31, v66
	v_mfma_f32_32x32x16_bf16 v[50:65], v[86:89], v[70:73], v[50:65]
	v_readlane_b32 s61, v255, 17
	v_ashrrev_i32_e32 v69, 31, v68
	v_lshlrev_b64 v[68:69], 2, v[68:69]
	s_add_i32 s2, s2, 1
	s_mov_b64 s[30:31], 0
	v_readlane_b32 s49, v255, 5
	v_readlane_b32 s50, v255, 6
	v_mfma_f32_32x32x16_bf16 v[34:49], v[94:97], v[70:73], v[34:49]
	v_lshlrev_b64 v[70:71], 12, v[66:67]
	v_lshl_add_u64 v[70:71], s[60:61], 0, v[70:71]
	v_lshl_add_u64 v[70:71], v[70:71], 0, v[68:69]
	v_readlane_b32 s51, v255, 7
	v_readlane_b32 s52, v255, 8
	v_readlane_b32 s53, v255, 9
	v_readlane_b32 s54, v255, 10
	v_mfma_f32_32x32x16_bf16 v[18:33], v[82:85], v[74:77], v[18:33]
	v_readlane_b32 s55, v255, 11
	v_readlane_b32 s56, v255, 12
	v_readlane_b32 s57, v255, 13
	v_readlane_b32 s58, v255, 14
	v_readlane_b32 s59, v255, 15
	v_readlane_b32 s62, v255, 18
	v_readlane_b32 s63, v255, 19
	v_mfma_f32_32x32x16_bf16 v[2:17], v[90:93], v[74:77], v[2:17]
	global_load_dwordx4 v[72:75], v[70:71], off
	v_lshlrev_b32_e32 v76, 16, v114
	v_and_b32_e32 v77, 0xffff0000, v114
	s_waitcnt vmcnt(0)
	v_fma_f32 v50, v50, v76, v72
	v_fma_f32 v51, v51, v77, v73
	v_lshlrev_b32_e32 v72, 16, v115
	v_and_b32_e32 v73, 0xffff0000, v115
	v_pk_fma_f32 v[52:53], v[52:53], v[72:73], v[74:75]
	global_store_dwordx4 v[70:71], v[50:53], off
	global_load_dwordx4 v[50:53], v[70:71], off offset:32
	v_lshlrev_b32_e32 v72, 16, v116
	v_and_b32_e32 v73, 0xffff0000, v116
	v_mfma_f32_32x32x16_bf16 v[18:33], v[86:89], v[78:81], v[18:33]
	s_waitcnt vmcnt(0)
	v_fma_f32 v50, v54, v72, v50
	v_fma_f32 v51, v55, v73, v51
	v_lshlrev_b32_e32 v54, 16, v117
	v_and_b32_e32 v55, 0xffff0000, v117
	v_pk_fma_f32 v[52:53], v[56:57], v[54:55], v[52:53]
	global_store_dwordx4 v[70:71], v[50:53], off offset:32
	global_load_dwordx4 v[50:53], v[70:71], off offset:64
	v_lshlrev_b32_e32 v54, 16, v118
	v_and_b32_e32 v55, 0xffff0000, v118
	v_mfma_f32_32x32x16_bf16 v[2:17], v[94:97], v[78:81], v[2:17]
	s_waitcnt vmcnt(0)
	v_fma_f32 v50, v58, v54, v50
	v_fma_f32 v51, v59, v55, v51
	v_lshlrev_b32_e32 v54, 16, v119
	v_and_b32_e32 v55, 0xffff0000, v119
	v_pk_fma_f32 v[52:53], v[60:61], v[54:55], v[52:53]
	global_store_dwordx4 v[70:71], v[50:53], off offset:64
	global_load_dwordx4 v[50:53], v[70:71], off offset:96
	v_lshlrev_b32_e32 v54, 16, v120
	v_and_b32_e32 v55, 0xffff0000, v120
	s_waitcnt vmcnt(0)
	v_pk_fma_f32 v[50:51], v[62:63], v[54:55], v[50:51]
	v_lshlrev_b32_e32 v54, 16, v121
	v_and_b32_e32 v55, 0xffff0000, v121
	v_pk_fma_f32 v[52:53], v[64:65], v[54:55], v[52:53]
	global_store_dwordx4 v[70:71], v[50:53], off offset:96
	global_load_dwordx4 v[50:53], v[70:71], off offset:128
	v_lshlrev_b32_e32 v54, 16, v122
	v_and_b32_e32 v55, 0xffff0000, v122
	s_waitcnt vmcnt(0)
	v_pk_fma_f32 v[34:35], v[34:35], v[54:55], v[50:51]
	v_lshlrev_b32_e32 v50, 16, v123
	v_and_b32_e32 v51, 0xffff0000, v123
	v_pk_fma_f32 v[36:37], v[36:37], v[50:51], v[52:53]
	global_store_dwordx4 v[70:71], v[34:37], off offset:128
	global_load_dwordx4 v[34:37], v[70:71], off offset:160
	v_lshlrev_b32_e32 v50, 16, v124
	v_and_b32_e32 v51, 0xffff0000, v124
	s_waitcnt vmcnt(0)
	v_pk_fma_f32 v[34:35], v[38:39], v[50:51], v[34:35]
	v_lshlrev_b32_e32 v38, 16, v125
	v_and_b32_e32 v39, 0xffff0000, v125
	v_pk_fma_f32 v[36:37], v[40:41], v[38:39], v[36:37]
	global_store_dwordx4 v[70:71], v[34:37], off offset:160
	global_load_dwordx4 v[34:37], v[70:71], off offset:192
	v_lshlrev_b32_e32 v38, 16, v126
	v_and_b32_e32 v39, 0xffff0000, v126
	v_lshlrev_b32_e32 v40, 16, v130
	v_and_b32_e32 v41, 0xffff0000, v130
	s_waitcnt vmcnt(0)
; DI float bf2f(u16 v) { return __uint_as_float((u32)v << 16); }
; __global__ void __launch_bounds__(512, 2) mega(Params P) {
;     ...
;         EPI_LOOP_BEGIN EPI_SWAP_IDX
;           f32x4* hp = reinterpret_cast<f32x4*>(H + (size_t)m * DM + nb);
;           f32x4 hv = *hp;
;           const u32 g01 = gatepk[mt][nt][2 * g], g23 = gatepk[mt][nt][2 * g + 1];
;           hv[0] += acc[mt][nt][4 * g] * bf2f((u16)(g01 & 0xffffu));
;           hv[1] += acc[mt][nt][4 * g + 1] * bf2f((u16)(g01 >> 16));
;           hv[2] += acc[mt][nt][4 * g + 2] * bf2f((u16)(g23 & 0xffffu));
;           hv[3] += acc[mt][nt][4 * g + 3] * bf2f((u16)(g23 >> 16));
;           *hp = hv;
;         EPI_LOOP_END
	v_pk_fma_f32 v[34:35], v[42:43], v[38:39], v[34:35]
	v_lshlrev_b32_e32 v38, 16, v127
	v_and_b32_e32 v39, 0xffff0000, v127
	v_pk_fma_f32 v[36:37], v[44:45], v[38:39], v[36:37]
	global_store_dwordx4 v[70:71], v[34:37], off offset:192
	global_load_dwordx4 v[34:37], v[70:71], off offset:224
	v_lshlrev_b32_e32 v38, 16, v128
	v_and_b32_e32 v39, 0xffff0000, v128
	s_waitcnt vmcnt(0)
	v_pk_fma_f32 v[34:35], v[46:47], v[38:39], v[34:35]
	v_lshlrev_b32_e32 v38, 16, v129
	v_and_b32_e32 v39, 0xffff0000, v129
	v_pk_fma_f32 v[36:37], v[48:49], v[38:39], v[36:37]
	global_store_dwordx4 v[70:71], v[34:37], off offset:224
	s_nop 1
	v_or_b32_e32 v34, 32, v66
	v_ashrrev_i32_e32 v35, 31, v34
	v_lshlrev_b64 v[34:35], 12, v[34:35]
	v_lshl_add_u64 v[34:35], s[60:61], 0, v[34:35]
	v_lshl_add_u64 v[34:35], v[34:35], 0, v[68:69]
	global_load_dwordx4 v[36:39], v[34:35], off
	s_waitcnt vmcnt(0)
	v_pk_fma_f32 v[18:19], v[18:19], v[40:41], v[36:37]
	v_lshlrev_b32_e32 v36, 16, v131
	v_and_b32_e32 v37, 0xffff0000, v131
	v_pk_fma_f32 v[20:21], v[20:21], v[36:37], v[38:39]
	global_store_dwordx4 v[34:35], v[18:21], off
	global_load_dwordx4 v[18:21], v[34:35], off offset:32
	v_lshlrev_b32_e32 v36, 16, v132
	v_and_b32_e32 v37, 0xffff0000, v132
	s_waitcnt vmcnt(0)
	v_pk_fma_f32 v[18:19], v[22:23], v[36:37], v[18:19]
	v_lshlrev_b32_e32 v22, 16, v133
	v_and_b32_e32 v23, 0xffff0000, v133
	v_pk_fma_f32 v[20:21], v[24:25], v[22:23], v[20:21]
	global_store_dwordx4 v[34:35], v[18:21], off offset:32
	global_load_dwordx4 v[18:21], v[34:35], off offset:64
	v_lshlrev_b32_e32 v22, 16, v134
	v_and_b32_e32 v23, 0xffff0000, v134
	s_waitcnt vmcnt(0)
	v_pk_fma_f32 v[18:19], v[26:27], v[22:23], v[18:19]
	v_lshlrev_b32_e32 v22, 16, v135
	v_and_b32_e32 v23, 0xffff0000, v135
	v_pk_fma_f32 v[20:21], v[28:29], v[22:23], v[20:21]
	global_store_dwordx4 v[34:35], v[18:21], off offset:64
	global_load_dwordx4 v[18:21], v[34:35], off offset:96
	v_lshlrev_b32_e32 v22, 16, v136
	v_and_b32_e32 v23, 0xffff0000, v136
	s_waitcnt vmcnt(0)
	v_pk_fma_f32 v[18:19], v[30:31], v[22:23], v[18:19]
	v_lshlrev_b32_e32 v22, 16, v137
	v_and_b32_e32 v23, 0xffff0000, v137
	v_pk_fma_f32 v[20:21], v[32:33], v[22:23], v[20:21]
	global_store_dwordx4 v[34:35], v[18:21], off offset:96
	global_load_dwordx4 v[18:21], v[34:35], off offset:128
	v_lshlrev_b32_e32 v22, 16, v140
	v_and_b32_e32 v23, 0xffff0000, v140
	s_waitcnt vmcnt(0)
	v_pk_fma_f32 v[2:3], v[2:3], v[22:23], v[18:19]
	v_lshlrev_b32_e32 v18, 16, v141
	v_and_b32_e32 v19, 0xffff0000, v141
	v_pk_fma_f32 v[4:5], v[4:5], v[18:19], v[20:21]
	global_store_dwordx4 v[34:35], v[2:5], off offset:128
	global_load_dwordx4 v[2:5], v[34:35], off offset:160
	v_lshlrev_b32_e32 v18, 16, v142
	v_and_b32_e32 v19, 0xffff0000, v142
	s_waitcnt vmcnt(0)
	v_pk_fma_f32 v[2:3], v[6:7], v[18:19], v[2:3]
	v_lshlrev_b32_e32 v6, 16, v143
	v_and_b32_e32 v7, 0xffff0000, v143
	v_pk_fma_f32 v[4:5], v[8:9], v[6:7], v[4:5]
	global_store_dwordx4 v[34:35], v[2:5], off offset:160
	global_load_dwordx4 v[2:5], v[34:35], off offset:192
	v_lshlrev_b32_e32 v6, 16, v144
	v_and_b32_e32 v7, 0xffff0000, v144
	s_waitcnt vmcnt(0)
	v_pk_fma_f32 v[2:3], v[10:11], v[6:7], v[2:3]
	v_lshlrev_b32_e32 v6, 16, v145
	v_and_b32_e32 v7, 0xffff0000, v145
	v_pk_fma_f32 v[4:5], v[12:13], v[6:7], v[4:5]
	global_store_dwordx4 v[34:35], v[2:5], off offset:192
	global_load_dwordx4 v[2:5], v[34:35], off offset:224
	v_lshlrev_b32_e32 v6, 16, v138
	v_and_b32_e32 v7, 0xffff0000, v138
	s_waitcnt vmcnt(0)
	v_pk_fma_f32 v[2:3], v[14:15], v[6:7], v[2:3]
	v_lshlrev_b32_e32 v6, 16, v139
	v_and_b32_e32 v7, 0xffff0000, v139
	v_pk_fma_f32 v[4:5], v[16:17], v[6:7], v[4:5]
	global_store_dwordx4 v[34:35], v[2:5], off offset:224
	s_branch .LBB0_1552

; __global__ void __launch_bounds__(512, 2) mega(Params P) {
;   cg::grid_group grid = cg::this_grid();
;   const int team = __builtin_amdgcn_readfirstlane((int)(threadIdx.x >> 8));
;   char* lds_raw = dyn_lds + team * TEAM_LDS;
	.amdhsa_kernel _Z4mega6Params
		.amdhsa_group_segment_fixed_size 28688
		.amdhsa_private_segment_fixed_size 0
		.amdhsa_kernarg_size 448
		.amdhsa_user_sgpr_count 2
		.amdhsa_user_sgpr_dispatch_ptr 0
		.amdhsa_user_sgpr_queue_ptr 0
		.amdhsa_user_sgpr_kernarg_segment_ptr 1
		.amdhsa_user_sgpr_dispatch_id 0
		.amdhsa_user_sgpr_kernarg_preload_length 0
		.amdhsa_user_sgpr_kernarg_preload_offset 0
		.amdhsa_user_sgpr_private_segment_size 0
		.amdhsa_uses_dynamic_stack 0
		.amdhsa_enable_private_segment 0
		.amdhsa_system_sgpr_workgroup_id_x 1
		.amdhsa_system_sgpr_workgroup_id_y 0
		.amdhsa_system_sgpr_workgroup_id_z 0
		.amdhsa_system_sgpr_workgroup_info 0
		.amdhsa_system_vgpr_workitem_id 2
		.amdhsa_next_free_vgpr 256
		.amdhsa_next_free_sgpr 102
		.amdhsa_accum_offset 256
		.amdhsa_reserve_vcc 1
		.amdhsa_float_round_mode_32 0
		.amdhsa_float_round_mode_16_64 0
		.amdhsa_float_denorm_mode_32 3
		.amdhsa_float_denorm_mode_16_64 3
		.amdhsa_dx10_clamp 1
		.amdhsa_ieee_mode 1
		.amdhsa_fp16_overflow 0
		.amdhsa_tg_split 0
		.amdhsa_exception_fp_ieee_invalid_op 0
		.amdhsa_exception_fp_denorm_src 0
		.amdhsa_exception_fp_ieee_div_zero 0
		.amdhsa_exception_fp_ieee_overflow 0
		.amdhsa_exception_fp_ieee_underflow 0
		.amdhsa_exception_fp_ieee_inexact 0
		.amdhsa_exception_int_div_zero 0
	.end_amdhsa_kernel

; __global__ void __launch_bounds__(512, 2) mega(Params P) {
;     ...
;   __shared__ uint4 xb_words;
amdhsa.kernels:
  - .agpr_count:     0
    .args:
      - .offset:         0
        .size:           192
        .value_kind:     by_value
      - .offset:         192
        .size:           4
        .value_kind:     hidden_block_count_x
      - .offset:         196
        .size:           4
        .value_kind:     hidden_block_count_y
      - .offset:         200
        .size:           4
        .value_kind:     hidden_block_count_z
      - .offset:         204
        .size:           2
        .value_kind:     hidden_group_size_x
      - .offset:         206
        .size:           2
        .value_kind:     hidden_group_size_y
      - .offset:         208
        .size:           2
        .value_kind:     hidden_group_size_z
      - .offset:         210
        .size:           2
        .value_kind:     hidden_remainder_x
      - .offset:         212
        .size:           2
        .value_kind:     hidden_remainder_y
      - .offset:         214
        .size:           2
        .value_kind:     hidden_remainder_z
      - .offset:         232
        .size:           8
        .value_kind:     hidden_global_offset_x
      - .offset:         240
        .size:           8
        .value_kind:     hidden_global_offset_y
      - .offset:         248
        .size:           8
        .value_kind:     hidden_global_offset_z
      - .offset:         256
        .size:           2
        .value_kind:     hidden_grid_dims
      - .offset:         280
        .size:           8
        .value_kind:     hidden_multigrid_sync_arg
      - .offset:         312
        .size:           4
        .value_kind:     hidden_dynamic_lds_size
    .group_segment_fixed_size: 28688
    .kernarg_segment_align: 8
    .kernarg_segment_size: 448
    .language:       OpenCL C
    .language_version:
      - 2
      - 0
    .max_flat_workgroup_size: 512
    .name:           _Z4mega6Params
    .private_segment_fixed_size: 0
    .sgpr_count:     108
    .sgpr_spill_count: 269
    .symbol:         _Z4mega6Params.kd
    .uniform_work_group_size: 1
    .uses_dynamic_stack: false
    .vgpr_count:     256
    .vgpr_spill_count: 0
    .wavefront_size: 64
